# as v40 but without the last-iteration prefetch-skip wrapper in the K-loops (3 fewer scalar/branch slots per load section)
# baseline (speedup 1.0000x reference)
; #define PG8_STAGE(bufoff, gbase, voff) do { _Pragma("unroll") for (int _i = 0; _i < 2; ++_i) \
;         __builtin_amdgcn_global_load_lds((const unsigned*)((const char*)(gbase) + (voff)[_i]), (LAS unsigned*)(lds + (bufoff) + ldsw + _i * 8192), 16, 0, 0); } while (0)
; #define PG8_LDA(dst, b, h) do { _Pragma("unroll") for (int m = 0; m < NM; ++m) _Pragma("unroll") for (int k = 0; k < 2; ++k) dst[m][k] = *(const LAS bf16x8*)(lds + PG8_SA(b, h) + aoff + m * 2048 + k * 1024); } while (0)
; #define PG8_LDB(dst, b, h) do { _Pragma("unroll") for (int n = 0; n < 2; ++n) _Pragma("unroll") for (int k = 0; k < 2; ++k) dst[n][k] = *(const LAS bf16x8*)(lds + PG8_SB(b, h) + boff + n * 2048 + k * 1024); } while (0)
; #define PG8_MMA(ai, bj, At, Bt) do { __builtin_amdgcn_s_setprio(1); _Pragma("unroll") for (int m = 0; m < NM; ++m) _Pragma("unroll") for (int n = 0; n < 2; ++n) _Pragma("unroll") for (int k = 0; k < 2; ++k) \
;         acc[ai][bj][m][n] = __builtin_amdgcn_mfma_f32_16x16x32_bf16(Bt[n][k], At[m][k], acc[ai][bj][m][n], 0, 0, 0); __builtin_amdgcn_s_setprio(0); } while (0)
; #define PG8_WAIT_V(n) asm volatile("s_waitcnt vmcnt(" #n ")" ::: "memory")
; #define PG8_WAIT_L(n) asm volatile("s_waitcnt lgkmcnt(" #n ")" ::: "memory")
; #define PG8_BAR __builtin_amdgcn_s_barrier()
; #define PG8_SCHED __builtin_amdgcn_sched_barrier(0)
;     ...
;             const bool last = (t == nt - 2);
;             const char* a1 = cA + (size_t)(t + 1) * kstep;
;             const char* a2 = last ? nA : cA + (size_t)(t + 2) * kstep; const char* b2 = last ? nB : cB + (size_t)(t + 2) * kstep;
;             const char* a3 = a2 + kstep; const char* b3 = b2 + kstep;
;             if constexpr (SP2) {
;             PG8_LDB(B0, 0, 0); PG8_LDB(B1, 0, 1); PG8_SCHED; PG8_LDA(At, 0, 0); PG8_STAGE(PG8_SA(1, 1), a1 + hstepA, voffA);
;             PG8_WAIT_V(8); PG8_WAIT_L(0); PG8_BAR; PG8_MMA(0, 0, At, B0); PG8_MMA(0, 1, At, B1); PG8_BAR; PG8_SCHED;
;             PG8_LDA(At, 0, 1); PG8_STAGE(PG8_SB(0, 0), b2, voffB); PG8_STAGE(PG8_SB(0, 1), b2 + hstepB, voffB); PG8_STAGE(PG8_SA(0, 0), a2, voffA);
;             PG8_WAIT_V(8); PG8_WAIT_L(0); PG8_BAR; PG8_MMA(1, 0, At, B0); PG8_MMA(1, 1, At, B1); PG8_BAR; PG8_SCHED;
.LBB0_200:
	ds_read_b128 v[26:29], v172
	ds_read_b128 v[30:33], v172 offset:1024
	ds_read_b128 v[42:45], v172 offset:2048
	ds_read_b128 v[46:49], v172 offset:3072
	ds_read_b128 v[146:149], v173
	ds_read_b128 v[150:153], v173 offset:1024
	ds_read_b128 v[164:167], v173 offset:2048
	ds_read_b128 v[168:171], v173 offset:3072
	s_add_u32 s30, s28, 0xfff80080
	s_addc_u32 s31, s29, -1
	s_cmp_eq_u32 s56, 28
	s_cselect_b32 s35, s2, s31
	s_cselect_b32 s34, s3, s30
	s_cselect_b32 s31, s9, s54
	s_cselect_b32 s30, s21, s23
	s_add_i32 m0, s43, 0xc000
	ds_read_b128 v[178:181], v174
	ds_read_b128 v[182:185], v174 offset:1024
	ds_read_b128 v[186:189], v174 offset:2048
	ds_read_b128 v[190:193], v174 offset:3072
	ds_read_b128 v[194:197], v174 offset:4096
	ds_read_b128 v[198:201], v174 offset:5120
	ds_read_b128 v[202:205], v174 offset:6144
	ds_read_b128 v[206:209], v174 offset:7168
	global_load_lds_dwordx4 v160, s[28:29]
	s_add_i32 m0, s43, 0xe000
	s_nop 0
	global_load_lds_dwordx4 v162, s[28:29]
	s_waitcnt vmcnt(8)
	s_waitcnt lgkmcnt(0)
	s_setprio 1
	s_barrier
	v_mfma_f32_16x16x32_bf16 v[142:145], v[26:29], v[178:181], v[142:145]
	v_mfma_f32_16x16x32_bf16 v[138:141], v[42:45], v[178:181], v[138:141]
	v_mfma_f32_16x16x32_bf16 v[126:129], v[26:29], v[186:189], v[126:129]
	v_mfma_f32_16x16x32_bf16 v[122:125], v[42:45], v[186:189], v[122:125]
	v_mfma_f32_16x16x32_bf16 v[110:113], v[26:29], v[194:197], v[110:113]
	v_mfma_f32_16x16x32_bf16 v[106:109], v[42:45], v[194:197], v[106:109]
	v_mfma_f32_16x16x32_bf16 v[94:97], v[26:29], v[202:205], v[94:97]
	v_mfma_f32_16x16x32_bf16 v[90:93], v[42:45], v[202:205], v[90:93]
	v_mfma_f32_16x16x32_bf16 v[142:145], v[30:33], v[182:185], v[142:145]
	v_mfma_f32_16x16x32_bf16 v[138:141], v[46:49], v[182:185], v[138:141]
	v_mfma_f32_16x16x32_bf16 v[126:129], v[30:33], v[190:193], v[126:129]
	v_mfma_f32_16x16x32_bf16 v[122:125], v[46:49], v[190:193], v[122:125]
	v_mfma_f32_16x16x32_bf16 v[110:113], v[30:33], v[198:201], v[110:113]
	v_mfma_f32_16x16x32_bf16 v[106:109], v[46:49], v[198:201], v[106:109]
	v_mfma_f32_16x16x32_bf16 v[94:97], v[30:33], v[206:209], v[94:97]
	v_mfma_f32_16x16x32_bf16 v[90:93], v[46:49], v[206:209], v[90:93]
	s_setprio 0
	s_setprio 1
	v_mfma_f32_16x16x32_bf16 v[134:137], v[146:149], v[178:181], v[134:137]
	v_mfma_f32_16x16x32_bf16 v[130:133], v[164:167], v[178:181], v[130:133]
	v_mfma_f32_16x16x32_bf16 v[118:121], v[146:149], v[186:189], v[118:121]
	v_mfma_f32_16x16x32_bf16 v[114:117], v[164:167], v[186:189], v[114:117]
	v_mfma_f32_16x16x32_bf16 v[102:105], v[146:149], v[194:197], v[102:105]
	v_mfma_f32_16x16x32_bf16 v[98:101], v[164:167], v[194:197], v[98:101]
	v_mfma_f32_16x16x32_bf16 v[86:89], v[146:149], v[202:205], v[86:89]
	v_mfma_f32_16x16x32_bf16 v[82:85], v[164:167], v[202:205], v[82:85]
	v_mfma_f32_16x16x32_bf16 v[134:137], v[150:153], v[182:185], v[134:137]
	v_mfma_f32_16x16x32_bf16 v[130:133], v[168:171], v[182:185], v[130:133]
	v_mfma_f32_16x16x32_bf16 v[118:121], v[150:153], v[190:193], v[118:121]
	v_mfma_f32_16x16x32_bf16 v[114:117], v[168:171], v[190:193], v[114:117]
	v_mfma_f32_16x16x32_bf16 v[102:105], v[150:153], v[198:201], v[102:105]
	v_mfma_f32_16x16x32_bf16 v[98:101], v[168:171], v[198:201], v[98:101]
	v_mfma_f32_16x16x32_bf16 v[86:89], v[150:153], v[206:209], v[86:89]
	v_mfma_f32_16x16x32_bf16 v[82:85], v[168:171], v[206:209], v[82:85]
	s_barrier
	s_setprio 0
	s_mov_b32 m0, s39
	v_lshl_add_u64 v[210:211], s[30:31], 0, v[0:1]
	s_add_u32 s72, s30, 0x80000
	ds_read_b128 v[178:181], v174 offset:16384
	ds_read_b128 v[182:185], v174 offset:17408
	ds_read_b128 v[186:189], v174 offset:18432
	ds_read_b128 v[190:193], v174 offset:19456
	ds_read_b128 v[194:197], v174 offset:20480
	ds_read_b128 v[198:201], v174 offset:21504
	ds_read_b128 v[202:205], v174 offset:22528
	ds_read_b128 v[206:209], v174 offset:23552
	global_load_lds_dwordx4 v0, s[30:31]
	v_lshl_add_u64 v[212:213], s[30:31], 0, v[158:159]
	s_mov_b32 m0, s40
	s_addc_u32 s73, s31, 0
	global_load_lds_dwordx4 v158, s[30:31]
	s_mov_b32 m0, s41
	v_lshl_add_u64 v[216:217], s[34:35], 0, v[156:157]
	global_load_lds_dwordx4 v0, s[72:73]
	s_mov_b32 m0, s42
	s_nop 0
	global_load_lds_dwordx4 v158, s[72:73]
	v_lshl_add_u64 v[214:215], s[34:35], 0, v[154:155]
	s_mov_b32 m0, s43
	s_nop 0
	global_load_lds_dwordx4 v154, s[34:35]
	s_mov_b32 m0, s44
	s_nop 0
	global_load_lds_dwordx4 v156, s[34:35]
	s_waitcnt vmcnt(8)
	s_waitcnt lgkmcnt(0)
	s_setprio 1
	s_barrier
	v_mfma_f32_16x16x32_bf16 v[78:81], v[26:29], v[178:181], v[78:81]
	v_mfma_f32_16x16x32_bf16 v[74:77], v[42:45], v[178:181], v[74:77]
	v_mfma_f32_16x16x32_bf16 v[62:65], v[26:29], v[186:189], v[62:65]
	v_mfma_f32_16x16x32_bf16 v[58:61], v[42:45], v[186:189], v[58:61]
	v_mfma_f32_16x16x32_bf16 v[38:41], v[26:29], v[194:197], v[38:41]
	v_mfma_f32_16x16x32_bf16 v[34:37], v[42:45], v[194:197], v[34:37]
	v_mfma_f32_16x16x32_bf16 v[14:17], v[26:29], v[202:205], v[14:17]
	v_mfma_f32_16x16x32_bf16 v[10:13], v[42:45], v[202:205], v[10:13]
	v_mfma_f32_16x16x32_bf16 v[78:81], v[30:33], v[182:185], v[78:81]
	v_mfma_f32_16x16x32_bf16 v[74:77], v[46:49], v[182:185], v[74:77]
	v_mfma_f32_16x16x32_bf16 v[62:65], v[30:33], v[190:193], v[62:65]
	v_mfma_f32_16x16x32_bf16 v[58:61], v[46:49], v[190:193], v[58:61]
	v_mfma_f32_16x16x32_bf16 v[38:41], v[30:33], v[198:201], v[38:41]
	v_mfma_f32_16x16x32_bf16 v[34:37], v[46:49], v[198:201], v[34:37]
	v_mfma_f32_16x16x32_bf16 v[14:17], v[30:33], v[206:209], v[14:17]
	v_mfma_f32_16x16x32_bf16 v[10:13], v[46:49], v[206:209], v[10:13]
	s_setprio 0
	s_setprio 1
	v_mfma_f32_16x16x32_bf16 v[22:25], v[146:149], v[194:197], v[22:25]
	v_mfma_f32_16x16x32_bf16 v[18:21], v[164:167], v[194:197], v[18:21]
	v_mfma_f32_16x16x32_bf16 v[6:9], v[146:149], v[202:205], v[6:9]
	v_mfma_f32_16x16x32_bf16 v[2:5], v[164:167], v[202:205], v[2:5]
	v_mfma_f32_16x16x32_bf16 v[26:29], v[146:149], v[178:181], v[70:73]
	v_mfma_f32_16x16x32_bf16 v[30:33], v[164:167], v[178:181], v[66:69]
	v_mfma_f32_16x16x32_bf16 v[42:45], v[146:149], v[186:189], v[54:57]
	v_mfma_f32_16x16x32_bf16 v[46:49], v[164:167], v[186:189], v[50:53]
	v_mfma_f32_16x16x32_bf16 v[22:25], v[150:153], v[198:201], v[22:25]
	v_mfma_f32_16x16x32_bf16 v[18:21], v[168:171], v[198:201], v[18:21]
	v_mfma_f32_16x16x32_bf16 v[6:9], v[150:153], v[206:209], v[6:9]
	v_mfma_f32_16x16x32_bf16 v[2:5], v[168:171], v[206:209], v[2:5]
	v_mfma_f32_16x16x32_bf16 v[26:29], v[150:153], v[182:185], v[26:29]
	v_mfma_f32_16x16x32_bf16 v[30:33], v[168:171], v[182:185], v[30:33]
	v_mfma_f32_16x16x32_bf16 v[42:45], v[150:153], v[190:193], v[42:45]
	v_mfma_f32_16x16x32_bf16 v[46:49], v[168:171], v[190:193], v[46:49]
	s_barrier
; #define PG8_STAGE(bufoff, gbase, voff) do { _Pragma("unroll") for (int _i = 0; _i < 2; ++_i) \
;         __builtin_amdgcn_global_load_lds((const unsigned*)((const char*)(gbase) + (voff)[_i]), (LAS unsigned*)(lds + (bufoff) + ldsw + _i * 8192), 16, 0, 0); } while (0)
; #define PG8_LDA(dst, b, h) do { _Pragma("unroll") for (int m = 0; m < NM; ++m) _Pragma("unroll") for (int k = 0; k < 2; ++k) dst[m][k] = *(const LAS bf16x8*)(lds + PG8_SA(b, h) + aoff + m * 2048 + k * 1024); } while (0)
; #define PG8_LDB(dst, b, h) do { _Pragma("unroll") for (int n = 0; n < 2; ++n) _Pragma("unroll") for (int k = 0; k < 2; ++k) dst[n][k] = *(const LAS bf16x8*)(lds + PG8_SB(b, h) + boff + n * 2048 + k * 1024); } while (0)
; #define PG8_MMA(ai, bj, At, Bt) do { __builtin_amdgcn_s_setprio(1); _Pragma("unroll") for (int m = 0; m < NM; ++m) _Pragma("unroll") for (int n = 0; n < 2; ++n) _Pragma("unroll") for (int k = 0; k < 2; ++k) \
;         acc[ai][bj][m][n] = __builtin_amdgcn_mfma_f32_16x16x32_bf16(Bt[n][k], At[m][k], acc[ai][bj][m][n], 0, 0, 0); __builtin_amdgcn_s_setprio(0); } while (0)
; #define PG8_WAIT_V(n) asm volatile("s_waitcnt vmcnt(" #n ")" ::: "memory")
; #define PG8_WAIT_L(n) asm volatile("s_waitcnt lgkmcnt(" #n ")" ::: "memory")
; #define PG8_BAR __builtin_amdgcn_s_barrier()
; #define PG8_SCHED __builtin_amdgcn_sched_barrier(0)
;     ...
;             PG8_LDB(B0, 1, 0); PG8_LDB(B1, 1, 1); PG8_SCHED; PG8_LDA(At, 1, 0); PG8_STAGE(PG8_SA(0, 1), a2 + hstepA, voffA);
;             PG8_WAIT_V(8); PG8_WAIT_L(0); PG8_BAR; PG8_MMA(0, 0, At, B0); PG8_MMA(0, 1, At, B1); PG8_BAR; PG8_SCHED;
;             PG8_LDA(At, 1, 1); PG8_STAGE(PG8_SB(1, 0), b3, voffB); PG8_STAGE(PG8_SB(1, 1), b3 + hstepB, voffB); PG8_STAGE(PG8_SA(1, 0), a3, voffA);
;             PG8_WAIT_V(8); PG8_WAIT_L(0); PG8_BAR; PG8_MMA(1, 0, At, B0); PG8_MMA(1, 1, At, B1); PG8_BAR; PG8_SCHED;
	s_setprio 0
	ds_read_b128 v[50:53], v175
	ds_read_b128 v[54:57], v175 offset:1024
	ds_read_b128 v[66:69], v175 offset:2048
	ds_read_b128 v[70:73], v175 offset:3072
	ds_read_b128 v[146:149], v176
	ds_read_b128 v[150:153], v176 offset:1024
	ds_read_b128 v[164:167], v176 offset:2048
	ds_read_b128 v[168:171], v176 offset:3072
	s_add_u32 s34, s34, 0x80000
	s_addc_u32 s35, s35, 0
	s_mov_b32 m0, s45
	ds_read_b128 v[178:181], v174 offset:32768
	ds_read_b128 v[182:185], v174 offset:33792
	ds_read_b128 v[186:189], v174 offset:34816
	ds_read_b128 v[190:193], v174 offset:35840
	ds_read_b128 v[194:197], v174 offset:36864
	ds_read_b128 v[198:201], v174 offset:37888
	ds_read_b128 v[202:205], v174 offset:38912
	ds_read_b128 v[206:209], v174 offset:39936
	global_load_lds_dwordx4 v154, s[34:35]
	s_mov_b32 m0, s46
	s_nop 0
	global_load_lds_dwordx4 v156, s[34:35]
	s_waitcnt vmcnt(8)
	s_waitcnt lgkmcnt(0)
	s_setprio 1
	s_barrier
	v_mfma_f32_16x16x32_bf16 v[142:145], v[50:53], v[178:181], v[142:145]
	v_mfma_f32_16x16x32_bf16 v[138:141], v[66:69], v[178:181], v[138:141]
	v_mfma_f32_16x16x32_bf16 v[126:129], v[50:53], v[186:189], v[126:129]
	v_mfma_f32_16x16x32_bf16 v[122:125], v[66:69], v[186:189], v[122:125]
	v_mfma_f32_16x16x32_bf16 v[110:113], v[50:53], v[194:197], v[110:113]
	v_mfma_f32_16x16x32_bf16 v[106:109], v[66:69], v[194:197], v[106:109]
	v_mfma_f32_16x16x32_bf16 v[94:97], v[50:53], v[202:205], v[94:97]
	v_mfma_f32_16x16x32_bf16 v[90:93], v[66:69], v[202:205], v[90:93]
	v_mfma_f32_16x16x32_bf16 v[142:145], v[54:57], v[182:185], v[142:145]
	v_mfma_f32_16x16x32_bf16 v[138:141], v[70:73], v[182:185], v[138:141]
	v_mfma_f32_16x16x32_bf16 v[126:129], v[54:57], v[190:193], v[126:129]
	v_mfma_f32_16x16x32_bf16 v[122:125], v[70:73], v[190:193], v[122:125]
	v_mfma_f32_16x16x32_bf16 v[110:113], v[54:57], v[198:201], v[110:113]
	v_mfma_f32_16x16x32_bf16 v[106:109], v[70:73], v[198:201], v[106:109]
	v_mfma_f32_16x16x32_bf16 v[94:97], v[54:57], v[206:209], v[94:97]
	v_mfma_f32_16x16x32_bf16 v[90:93], v[70:73], v[206:209], v[90:93]
	s_setprio 0
	s_setprio 1
	v_mfma_f32_16x16x32_bf16 v[134:137], v[146:149], v[178:181], v[134:137]
	v_mfma_f32_16x16x32_bf16 v[130:133], v[164:167], v[178:181], v[130:133]
	v_mfma_f32_16x16x32_bf16 v[118:121], v[146:149], v[186:189], v[118:121]
	v_mfma_f32_16x16x32_bf16 v[114:117], v[164:167], v[186:189], v[114:117]
	v_mfma_f32_16x16x32_bf16 v[102:105], v[146:149], v[194:197], v[102:105]
	v_mfma_f32_16x16x32_bf16 v[98:101], v[164:167], v[194:197], v[98:101]
	v_mfma_f32_16x16x32_bf16 v[86:89], v[146:149], v[202:205], v[86:89]
	v_mfma_f32_16x16x32_bf16 v[82:85], v[164:167], v[202:205], v[82:85]
	v_mfma_f32_16x16x32_bf16 v[134:137], v[150:153], v[182:185], v[134:137]
	v_mfma_f32_16x16x32_bf16 v[130:133], v[168:171], v[182:185], v[130:133]
	v_mfma_f32_16x16x32_bf16 v[118:121], v[150:153], v[190:193], v[118:121]
	v_mfma_f32_16x16x32_bf16 v[114:117], v[168:171], v[190:193], v[114:117]
	v_mfma_f32_16x16x32_bf16 v[102:105], v[150:153], v[198:201], v[102:105]
	v_mfma_f32_16x16x32_bf16 v[98:101], v[168:171], v[198:201], v[98:101]
	v_mfma_f32_16x16x32_bf16 v[86:89], v[150:153], v[206:209], v[86:89]
	v_mfma_f32_16x16x32_bf16 v[82:85], v[168:171], v[206:209], v[82:85]
	s_barrier
	s_setprio 0
	s_mov_b32 m0, s49
	v_lshl_add_u64 v[210:211], v[210:211], 0, s[66:67]
	s_add_u32 s30, s30, 0x80080
	ds_read_b128 v[178:181], v174 offset:49152
	ds_read_b128 v[182:185], v174 offset:50176
	ds_read_b128 v[186:189], v174 offset:51200
	ds_read_b128 v[190:193], v174 offset:52224
	ds_read_b128 v[194:197], v174 offset:53248
	ds_read_b128 v[198:201], v174 offset:54272
	ds_read_b128 v[202:205], v174 offset:55296
	ds_read_b128 v[206:209], v174 offset:56320
	global_load_lds_dwordx4 v[210:211], off
	v_lshl_add_u64 v[210:211], v[212:213], 0, s[66:67]
	s_mov_b32 m0, s50
	s_addc_u32 s31, s31, 0
	global_load_lds_dwordx4 v[210:211], off
	s_mov_b32 m0, s58
	s_nop 0
	global_load_lds_dwordx4 v0, s[30:31]
	s_mov_b32 m0, s59
	s_nop 0
	global_load_lds_dwordx4 v158, s[30:31]
	v_lshl_add_u64 v[210:211], v[214:215], 0, s[66:67]
	s_mov_b32 m0, s51
	s_nop 0
	global_load_lds_dwordx4 v[210:211], off
	v_lshl_add_u64 v[210:211], v[216:217], 0, s[66:67]
	s_mov_b32 m0, s52
	s_nop 0
	global_load_lds_dwordx4 v[210:211], off
	s_waitcnt vmcnt(8)
	s_waitcnt lgkmcnt(0)
	s_setprio 1
	s_barrier
	v_mfma_f32_16x16x32_bf16 v[78:81], v[50:53], v[178:181], v[78:81]
	v_mfma_f32_16x16x32_bf16 v[74:77], v[66:69], v[178:181], v[74:77]
	v_mfma_f32_16x16x32_bf16 v[62:65], v[50:53], v[186:189], v[62:65]
	v_mfma_f32_16x16x32_bf16 v[58:61], v[66:69], v[186:189], v[58:61]
	v_mfma_f32_16x16x32_bf16 v[38:41], v[50:53], v[194:197], v[38:41]
	v_mfma_f32_16x16x32_bf16 v[34:37], v[66:69], v[194:197], v[34:37]
	v_mfma_f32_16x16x32_bf16 v[14:17], v[50:53], v[202:205], v[14:17]
	v_mfma_f32_16x16x32_bf16 v[10:13], v[66:69], v[202:205], v[10:13]
	v_mfma_f32_16x16x32_bf16 v[78:81], v[54:57], v[182:185], v[78:81]
	v_mfma_f32_16x16x32_bf16 v[74:77], v[70:73], v[182:185], v[74:77]
	v_mfma_f32_16x16x32_bf16 v[62:65], v[54:57], v[190:193], v[62:65]
	v_mfma_f32_16x16x32_bf16 v[58:61], v[70:73], v[190:193], v[58:61]
	v_mfma_f32_16x16x32_bf16 v[38:41], v[54:57], v[198:201], v[38:41]
	v_mfma_f32_16x16x32_bf16 v[34:37], v[70:73], v[198:201], v[34:37]
	v_mfma_f32_16x16x32_bf16 v[14:17], v[54:57], v[206:209], v[14:17]
	v_mfma_f32_16x16x32_bf16 v[10:13], v[70:73], v[206:209], v[10:13]
	s_setprio 0
	s_setprio 1
	v_mfma_f32_16x16x32_bf16 v[26:29], v[146:149], v[178:181], v[26:29]
	v_mfma_f32_16x16x32_bf16 v[70:73], v[150:153], v[182:185], v[26:29]
	v_mfma_f32_16x16x32_bf16 v[26:29], v[164:167], v[178:181], v[30:33]
	v_mfma_f32_16x16x32_bf16 v[66:69], v[168:171], v[182:185], v[26:29]
	v_mfma_f32_16x16x32_bf16 v[26:29], v[146:149], v[186:189], v[42:45]
	v_mfma_f32_16x16x32_bf16 v[54:57], v[150:153], v[190:193], v[26:29]
	v_mfma_f32_16x16x32_bf16 v[26:29], v[164:167], v[186:189], v[46:49]
	v_mfma_f32_16x16x32_bf16 v[22:25], v[146:149], v[194:197], v[22:25]
	v_mfma_f32_16x16x32_bf16 v[18:21], v[164:167], v[194:197], v[18:21]
	v_mfma_f32_16x16x32_bf16 v[6:9], v[146:149], v[202:205], v[6:9]
	v_mfma_f32_16x16x32_bf16 v[2:5], v[164:167], v[202:205], v[2:5]
	v_mfma_f32_16x16x32_bf16 v[50:53], v[168:171], v[190:193], v[26:29]
	v_mfma_f32_16x16x32_bf16 v[22:25], v[150:153], v[198:201], v[22:25]
	v_mfma_f32_16x16x32_bf16 v[18:21], v[168:171], v[198:201], v[18:21]
	v_mfma_f32_16x16x32_bf16 v[6:9], v[150:153], v[206:209], v[6:9]
	v_mfma_f32_16x16x32_bf16 v[2:5], v[168:171], v[206:209], v[2:5]
	s_barrier
	s_setprio 0
	s_add_i32 s56, s56, 2
	s_add_u32 s28, s28, 0x100
	s_addc_u32 s29, s29, 0
	s_add_u32 s23, s23, 0x100
	s_addc_u32 s54, s54, 0
	s_cmp_gt_u32 s56, 29
	s_cbranch_scc0 .LBB0_200
	s_and_b64 vcc, exec, s[14:15]
	s_cbranch_vccz .LBB0_203
	s_barrier

; #define PG8_STAGE(bufoff, gbase, voff) do { _Pragma("unroll") for (int _i = 0; _i < 2; ++_i) \
;         __builtin_amdgcn_global_load_lds((const unsigned*)((const char*)(gbase) + (voff)[_i]), (LAS unsigned*)(lds + (bufoff) + ldsw + _i * 8192), 16, 0, 0); } while (0)
; #define PG8_LDA(dst, b, h) do { _Pragma("unroll") for (int m = 0; m < NM; ++m) _Pragma("unroll") for (int k = 0; k < 2; ++k) dst[m][k] = *(const LAS bf16x8*)(lds + PG8_SA(b, h) + aoff + m * 2048 + k * 1024); } while (0)
; #define PG8_LDB(dst, b, h) do { _Pragma("unroll") for (int n = 0; n < 2; ++n) _Pragma("unroll") for (int k = 0; k < 2; ++k) dst[n][k] = *(const LAS bf16x8*)(lds + PG8_SB(b, h) + boff + n * 2048 + k * 1024); } while (0)
; #define PG8_MMA(ai, bj, At, Bt) do { __builtin_amdgcn_s_setprio(1); _Pragma("unroll") for (int m = 0; m < NM; ++m) _Pragma("unroll") for (int n = 0; n < 2; ++n) _Pragma("unroll") for (int k = 0; k < 2; ++k) \
;         acc[ai][bj][m][n] = __builtin_amdgcn_mfma_f32_16x16x32_bf16(Bt[n][k], At[m][k], acc[ai][bj][m][n], 0, 0, 0); __builtin_amdgcn_s_setprio(0); } while (0)
; #define PG8_WAIT_V(n) asm volatile("s_waitcnt vmcnt(" #n ")" ::: "memory")
; #define PG8_WAIT_L(n) asm volatile("s_waitcnt lgkmcnt(" #n ")" ::: "memory")
; #define PG8_BAR __builtin_amdgcn_s_barrier()
; #define PG8_SCHED __builtin_amdgcn_sched_barrier(0)
;     ...
;             const bool last = (t == nt - 2);
;             const char* a1 = cA + (size_t)(t + 1) * kstep;
;             const char* a2 = last ? nA : cA + (size_t)(t + 2) * kstep; const char* b2 = last ? nB : cB + (size_t)(t + 2) * kstep;
;             const char* a3 = a2 + kstep; const char* b3 = b2 + kstep;
;             if constexpr (SP2) {
;             PG8_LDB(B0, 0, 0); PG8_LDB(B1, 0, 1); PG8_SCHED; PG8_LDA(At, 0, 0); PG8_STAGE(PG8_SA(1, 1), a1 + hstepA, voffA);
;             PG8_WAIT_V(8); PG8_WAIT_L(0); PG8_BAR; PG8_MMA(0, 0, At, B0); PG8_MMA(0, 1, At, B1); PG8_BAR; PG8_SCHED;
;             PG8_LDA(At, 0, 1); PG8_STAGE(PG8_SB(0, 0), b2, voffB); PG8_STAGE(PG8_SB(0, 1), b2 + hstepB, voffB); PG8_STAGE(PG8_SA(0, 0), a2, voffA);
;             PG8_WAIT_V(8); PG8_WAIT_L(0); PG8_BAR; PG8_MMA(1, 0, At, B0); PG8_MMA(1, 1, At, B1); PG8_BAR; PG8_SCHED;
.LBB0_703:
	v_add_u32_e32 v0, s50, v146
	ds_read_b128 v[138:141], v0
	ds_read_b128 v[142:145], v0 offset:1024
	ds_read_b128 v[148:151], v0 offset:2048
	ds_read_b128 v[152:155], v0 offset:3072
	v_add_u32_e32 v0, s54, v146
	ds_read_b128 v[156:159], v0
	ds_read_b128 v[160:163], v0 offset:1024
	ds_read_b128 v[164:167], v0 offset:2048
	ds_read_b128 v[168:171], v0 offset:3072
	s_add_u32 s12, s10, 0xfff80080
	s_addc_u32 s13, s11, -1
	s_cmp_eq_u32 s39, 28
	s_cselect_b32 s37, s2, s13
	s_cselect_b32 s36, s3, s12
	s_cselect_b32 s13, s9, s38
	s_cselect_b32 s12, s27, s29
	s_add_i32 m0, s58, 0xc000
	ds_read_b128 v[172:175], v147
	ds_read_b128 v[176:179], v147 offset:1024
	ds_read_b128 v[180:183], v147 offset:2048
	ds_read_b128 v[184:187], v147 offset:3072
	ds_read_b128 v[188:191], v147 offset:4096
	ds_read_b128 v[192:195], v147 offset:5120
	ds_read_b128 v[196:199], v147 offset:6144
	ds_read_b128 v[200:203], v147 offset:7168
	global_load_lds_dwordx4 v134, s[10:11]
	s_add_i32 m0, s58, 0xe000
	s_nop 0
	global_load_lds_dwordx4 v136, s[10:11]
	s_waitcnt vmcnt(8)
	s_waitcnt lgkmcnt(0)
	s_setprio 1
	s_barrier
	v_mfma_f32_16x16x32_bf16 v[126:129], v[138:141], v[172:175], v[126:129]
	v_mfma_f32_16x16x32_bf16 v[122:125], v[148:151], v[172:175], v[122:125]
	v_mfma_f32_16x16x32_bf16 v[110:113], v[138:141], v[180:183], v[110:113]
	v_mfma_f32_16x16x32_bf16 v[106:109], v[148:151], v[180:183], v[106:109]
	v_mfma_f32_16x16x32_bf16 v[94:97], v[138:141], v[188:191], v[94:97]
	v_mfma_f32_16x16x32_bf16 v[90:93], v[148:151], v[188:191], v[90:93]
	v_mfma_f32_16x16x32_bf16 v[78:81], v[138:141], v[196:199], v[78:81]
	v_mfma_f32_16x16x32_bf16 v[74:77], v[148:151], v[196:199], v[74:77]
	v_mfma_f32_16x16x32_bf16 v[126:129], v[142:145], v[176:179], v[126:129]
	v_mfma_f32_16x16x32_bf16 v[122:125], v[152:155], v[176:179], v[122:125]
	v_mfma_f32_16x16x32_bf16 v[110:113], v[142:145], v[184:187], v[110:113]
	v_mfma_f32_16x16x32_bf16 v[106:109], v[152:155], v[184:187], v[106:109]
	v_mfma_f32_16x16x32_bf16 v[94:97], v[142:145], v[192:195], v[94:97]
	v_mfma_f32_16x16x32_bf16 v[90:93], v[152:155], v[192:195], v[90:93]
	v_mfma_f32_16x16x32_bf16 v[78:81], v[142:145], v[200:203], v[78:81]
	v_mfma_f32_16x16x32_bf16 v[74:77], v[152:155], v[200:203], v[74:77]
	s_setprio 0
	s_setprio 1
	v_mfma_f32_16x16x32_bf16 v[118:121], v[156:159], v[172:175], v[118:121]
	v_mfma_f32_16x16x32_bf16 v[114:117], v[164:167], v[172:175], v[114:117]
	v_mfma_f32_16x16x32_bf16 v[102:105], v[156:159], v[180:183], v[102:105]
	v_mfma_f32_16x16x32_bf16 v[98:101], v[164:167], v[180:183], v[98:101]
	v_mfma_f32_16x16x32_bf16 v[86:89], v[156:159], v[188:191], v[86:89]
	v_mfma_f32_16x16x32_bf16 v[82:85], v[164:167], v[188:191], v[82:85]
	v_mfma_f32_16x16x32_bf16 v[70:73], v[156:159], v[196:199], v[70:73]
	v_mfma_f32_16x16x32_bf16 v[66:69], v[164:167], v[196:199], v[66:69]
	v_mfma_f32_16x16x32_bf16 v[118:121], v[160:163], v[176:179], v[118:121]
	v_mfma_f32_16x16x32_bf16 v[114:117], v[168:171], v[176:179], v[114:117]
	v_mfma_f32_16x16x32_bf16 v[102:105], v[160:163], v[184:187], v[102:105]
	v_mfma_f32_16x16x32_bf16 v[98:101], v[168:171], v[184:187], v[98:101]
	v_mfma_f32_16x16x32_bf16 v[86:89], v[160:163], v[192:195], v[86:89]
	v_mfma_f32_16x16x32_bf16 v[82:85], v[168:171], v[192:195], v[82:85]
	v_mfma_f32_16x16x32_bf16 v[70:73], v[160:163], v[200:203], v[70:73]
	v_mfma_f32_16x16x32_bf16 v[66:69], v[168:171], v[200:203], v[66:69]
	s_barrier
	s_setprio 0
	s_mov_b32 m0, s51
	v_lshl_add_u64 v[204:205], s[12:13], 0, v[130:131]
	s_add_u32 s40, s12, 0x80000
	ds_read_b128 v[172:175], v147 offset:16384
	ds_read_b128 v[176:179], v147 offset:17408
	ds_read_b128 v[180:183], v147 offset:18432
	ds_read_b128 v[184:187], v147 offset:19456
	ds_read_b128 v[188:191], v147 offset:20480
	ds_read_b128 v[192:195], v147 offset:21504
	ds_read_b128 v[196:199], v147 offset:22528
	ds_read_b128 v[200:203], v147 offset:23552
	global_load_lds_dwordx4 v130, s[12:13]
	v_lshl_add_u64 v[206:207], s[12:13], 0, v[132:133]
	s_mov_b32 m0, s52
	s_addc_u32 s41, s13, 0
	global_load_lds_dwordx4 v132, s[12:13]
	s_mov_b32 m0, s56
	v_lshl_add_u64 v[210:211], s[36:37], 0, v[132:133]
	global_load_lds_dwordx4 v130, s[40:41]
	s_mov_b32 m0, s57
	s_nop 0
	global_load_lds_dwordx4 v132, s[40:41]
	v_lshl_add_u64 v[208:209], s[36:37], 0, v[130:131]
	s_mov_b32 m0, s58
	s_nop 0
	global_load_lds_dwordx4 v130, s[36:37]
	s_mov_b32 m0, s59
	s_nop 0
	global_load_lds_dwordx4 v132, s[36:37]
	s_waitcnt vmcnt(8)
	s_waitcnt lgkmcnt(0)
	s_setprio 1
	s_barrier
	v_mfma_f32_16x16x32_bf16 v[62:65], v[138:141], v[172:175], v[62:65]
	v_mfma_f32_16x16x32_bf16 v[58:61], v[148:151], v[172:175], v[58:61]
	v_mfma_f32_16x16x32_bf16 v[46:49], v[138:141], v[180:183], v[46:49]
	v_mfma_f32_16x16x32_bf16 v[42:45], v[148:151], v[180:183], v[42:45]
	v_mfma_f32_16x16x32_bf16 v[30:33], v[138:141], v[188:191], v[30:33]
	v_mfma_f32_16x16x32_bf16 v[26:29], v[148:151], v[188:191], v[26:29]
	v_mfma_f32_16x16x32_bf16 v[14:17], v[138:141], v[196:199], v[14:17]
	v_mfma_f32_16x16x32_bf16 v[10:13], v[148:151], v[196:199], v[10:13]
	v_mfma_f32_16x16x32_bf16 v[62:65], v[142:145], v[176:179], v[62:65]
	v_mfma_f32_16x16x32_bf16 v[58:61], v[152:155], v[176:179], v[58:61]
	v_mfma_f32_16x16x32_bf16 v[46:49], v[142:145], v[184:187], v[46:49]
	v_mfma_f32_16x16x32_bf16 v[42:45], v[152:155], v[184:187], v[42:45]
	v_mfma_f32_16x16x32_bf16 v[30:33], v[142:145], v[192:195], v[30:33]
	v_mfma_f32_16x16x32_bf16 v[26:29], v[152:155], v[192:195], v[26:29]
	v_mfma_f32_16x16x32_bf16 v[14:17], v[142:145], v[200:203], v[14:17]
	v_mfma_f32_16x16x32_bf16 v[10:13], v[152:155], v[200:203], v[10:13]
	s_setprio 0
	s_setprio 1
	v_mfma_f32_16x16x32_bf16 v[54:57], v[156:159], v[172:175], v[54:57]
	v_mfma_f32_16x16x32_bf16 v[50:53], v[164:167], v[172:175], v[50:53]
	v_mfma_f32_16x16x32_bf16 v[38:41], v[156:159], v[180:183], v[38:41]
	v_mfma_f32_16x16x32_bf16 v[34:37], v[164:167], v[180:183], v[34:37]
	v_mfma_f32_16x16x32_bf16 v[22:25], v[156:159], v[188:191], v[22:25]
	v_mfma_f32_16x16x32_bf16 v[18:21], v[164:167], v[188:191], v[18:21]
	v_mfma_f32_16x16x32_bf16 v[6:9], v[156:159], v[196:199], v[6:9]
	v_mfma_f32_16x16x32_bf16 v[2:5], v[164:167], v[196:199], v[2:5]
	v_mfma_f32_16x16x32_bf16 v[54:57], v[160:163], v[176:179], v[54:57]
	v_mfma_f32_16x16x32_bf16 v[50:53], v[168:171], v[176:179], v[50:53]
	v_mfma_f32_16x16x32_bf16 v[38:41], v[160:163], v[184:187], v[38:41]
	v_mfma_f32_16x16x32_bf16 v[34:37], v[168:171], v[184:187], v[34:37]
	v_mfma_f32_16x16x32_bf16 v[22:25], v[160:163], v[192:195], v[22:25]
	v_mfma_f32_16x16x32_bf16 v[18:21], v[168:171], v[192:195], v[18:21]
	v_mfma_f32_16x16x32_bf16 v[6:9], v[160:163], v[200:203], v[6:9]
	v_mfma_f32_16x16x32_bf16 v[2:5], v[168:171], v[200:203], v[2:5]
	s_barrier
; #define PG8_STAGE(bufoff, gbase, voff) do { _Pragma("unroll") for (int _i = 0; _i < 2; ++_i) \
;         __builtin_amdgcn_global_load_lds((const unsigned*)((const char*)(gbase) + (voff)[_i]), (LAS unsigned*)(lds + (bufoff) + ldsw + _i * 8192), 16, 0, 0); } while (0)
; #define PG8_LDA(dst, b, h) do { _Pragma("unroll") for (int m = 0; m < NM; ++m) _Pragma("unroll") for (int k = 0; k < 2; ++k) dst[m][k] = *(const LAS bf16x8*)(lds + PG8_SA(b, h) + aoff + m * 2048 + k * 1024); } while (0)
; #define PG8_LDB(dst, b, h) do { _Pragma("unroll") for (int n = 0; n < 2; ++n) _Pragma("unroll") for (int k = 0; k < 2; ++k) dst[n][k] = *(const LAS bf16x8*)(lds + PG8_SB(b, h) + boff + n * 2048 + k * 1024); } while (0)
; #define PG8_MMA(ai, bj, At, Bt) do { __builtin_amdgcn_s_setprio(1); _Pragma("unroll") for (int m = 0; m < NM; ++m) _Pragma("unroll") for (int n = 0; n < 2; ++n) _Pragma("unroll") for (int k = 0; k < 2; ++k) \
;         acc[ai][bj][m][n] = __builtin_amdgcn_mfma_f32_16x16x32_bf16(Bt[n][k], At[m][k], acc[ai][bj][m][n], 0, 0, 0); __builtin_amdgcn_s_setprio(0); } while (0)
; #define PG8_WAIT_V(n) asm volatile("s_waitcnt vmcnt(" #n ")" ::: "memory")
; #define PG8_WAIT_L(n) asm volatile("s_waitcnt lgkmcnt(" #n ")" ::: "memory")
; #define PG8_BAR __builtin_amdgcn_s_barrier()
; #define PG8_SCHED __builtin_amdgcn_sched_barrier(0)
;     ...
;             PG8_LDB(B0, 1, 0); PG8_LDB(B1, 1, 1); PG8_SCHED; PG8_LDA(At, 1, 0); PG8_STAGE(PG8_SA(0, 1), a2 + hstepA, voffA);
;             PG8_WAIT_V(8); PG8_WAIT_L(0); PG8_BAR; PG8_MMA(0, 0, At, B0); PG8_MMA(0, 1, At, B1); PG8_BAR; PG8_SCHED;
;             PG8_LDA(At, 1, 1); PG8_STAGE(PG8_SB(1, 0), b3, voffB); PG8_STAGE(PG8_SB(1, 1), b3 + hstepB, voffB); PG8_STAGE(PG8_SA(1, 0), a3, voffA);
;             PG8_WAIT_V(8); PG8_WAIT_L(0); PG8_BAR; PG8_MMA(1, 0, At, B0); PG8_MMA(1, 1, At, B1); PG8_BAR; PG8_SCHED;
	s_setprio 0
	v_add_u32_e32 v0, s64, v146
	ds_read_b128 v[138:141], v0
	ds_read_b128 v[142:145], v0 offset:1024
	ds_read_b128 v[148:151], v0 offset:2048
	ds_read_b128 v[152:155], v0 offset:3072
	v_add_u32_e32 v0, s71, v146
	ds_read_b128 v[156:159], v0
	ds_read_b128 v[160:163], v0 offset:1024
	ds_read_b128 v[164:167], v0 offset:2048
	ds_read_b128 v[168:171], v0 offset:3072
	s_add_u32 s36, s36, 0x80000
	s_addc_u32 s37, s37, 0
	s_mov_b32 m0, s62
	ds_read_b128 v[172:175], v147 offset:32768
	ds_read_b128 v[176:179], v147 offset:33792
	ds_read_b128 v[180:183], v147 offset:34816
	ds_read_b128 v[184:187], v147 offset:35840
	ds_read_b128 v[188:191], v147 offset:36864
	ds_read_b128 v[192:195], v147 offset:37888
	ds_read_b128 v[196:199], v147 offset:38912
	ds_read_b128 v[200:203], v147 offset:39936
	global_load_lds_dwordx4 v130, s[36:37]
	s_mov_b32 m0, s63
	s_nop 0
	global_load_lds_dwordx4 v132, s[36:37]
	s_waitcnt vmcnt(8)
	s_waitcnt lgkmcnt(0)
	s_setprio 1
	s_barrier
	v_mfma_f32_16x16x32_bf16 v[126:129], v[138:141], v[172:175], v[126:129]
	v_mfma_f32_16x16x32_bf16 v[122:125], v[148:151], v[172:175], v[122:125]
	v_mfma_f32_16x16x32_bf16 v[110:113], v[138:141], v[180:183], v[110:113]
	v_mfma_f32_16x16x32_bf16 v[106:109], v[148:151], v[180:183], v[106:109]
	v_mfma_f32_16x16x32_bf16 v[94:97], v[138:141], v[188:191], v[94:97]
	v_mfma_f32_16x16x32_bf16 v[90:93], v[148:151], v[188:191], v[90:93]
	v_mfma_f32_16x16x32_bf16 v[78:81], v[138:141], v[196:199], v[78:81]
	v_mfma_f32_16x16x32_bf16 v[74:77], v[148:151], v[196:199], v[74:77]
	v_mfma_f32_16x16x32_bf16 v[126:129], v[142:145], v[176:179], v[126:129]
	v_mfma_f32_16x16x32_bf16 v[122:125], v[152:155], v[176:179], v[122:125]
	v_mfma_f32_16x16x32_bf16 v[110:113], v[142:145], v[184:187], v[110:113]
	v_mfma_f32_16x16x32_bf16 v[106:109], v[152:155], v[184:187], v[106:109]
	v_mfma_f32_16x16x32_bf16 v[94:97], v[142:145], v[192:195], v[94:97]
	v_mfma_f32_16x16x32_bf16 v[90:93], v[152:155], v[192:195], v[90:93]
	v_mfma_f32_16x16x32_bf16 v[78:81], v[142:145], v[200:203], v[78:81]
	v_mfma_f32_16x16x32_bf16 v[74:77], v[152:155], v[200:203], v[74:77]
	s_setprio 0
	s_setprio 1
	v_mfma_f32_16x16x32_bf16 v[118:121], v[156:159], v[172:175], v[118:121]
	v_mfma_f32_16x16x32_bf16 v[114:117], v[164:167], v[172:175], v[114:117]
	v_mfma_f32_16x16x32_bf16 v[102:105], v[156:159], v[180:183], v[102:105]
	v_mfma_f32_16x16x32_bf16 v[98:101], v[164:167], v[180:183], v[98:101]
	v_mfma_f32_16x16x32_bf16 v[86:89], v[156:159], v[188:191], v[86:89]
	v_mfma_f32_16x16x32_bf16 v[82:85], v[164:167], v[188:191], v[82:85]
	v_mfma_f32_16x16x32_bf16 v[70:73], v[156:159], v[196:199], v[70:73]
	v_mfma_f32_16x16x32_bf16 v[66:69], v[164:167], v[196:199], v[66:69]
	v_mfma_f32_16x16x32_bf16 v[118:121], v[160:163], v[176:179], v[118:121]
	v_mfma_f32_16x16x32_bf16 v[114:117], v[168:171], v[176:179], v[114:117]
	v_mfma_f32_16x16x32_bf16 v[102:105], v[160:163], v[184:187], v[102:105]
	v_mfma_f32_16x16x32_bf16 v[98:101], v[168:171], v[184:187], v[98:101]
	v_mfma_f32_16x16x32_bf16 v[86:89], v[160:163], v[192:195], v[86:89]
	v_mfma_f32_16x16x32_bf16 v[82:85], v[168:171], v[192:195], v[82:85]
	v_mfma_f32_16x16x32_bf16 v[70:73], v[160:163], v[200:203], v[70:73]
	v_mfma_f32_16x16x32_bf16 v[66:69], v[168:171], v[200:203], v[66:69]
	s_barrier
	s_setprio 0
	s_mov_b32 m0, s65
	v_lshl_add_u64 v[204:205], v[204:205], 0, s[66:67]
	s_add_u32 s12, s12, 0x80080
	ds_read_b128 v[172:175], v147 offset:49152
	ds_read_b128 v[176:179], v147 offset:50176
	ds_read_b128 v[180:183], v147 offset:51200
	ds_read_b128 v[184:187], v147 offset:52224
	ds_read_b128 v[188:191], v147 offset:53248
	ds_read_b128 v[192:195], v147 offset:54272
	ds_read_b128 v[196:199], v147 offset:55296
	ds_read_b128 v[200:203], v147 offset:56320
	global_load_lds_dwordx4 v[204:205], off
	v_lshl_add_u64 v[204:205], v[206:207], 0, s[66:67]
	s_mov_b32 m0, s68
	s_addc_u32 s13, s13, 0
	global_load_lds_dwordx4 v[204:205], off
	s_mov_b32 m0, s72
	s_nop 0
	global_load_lds_dwordx4 v130, s[12:13]
	s_mov_b32 m0, s73
	s_nop 0
	global_load_lds_dwordx4 v132, s[12:13]
	v_lshl_add_u64 v[204:205], v[208:209], 0, s[66:67]
	s_mov_b32 m0, s69
	s_nop 0
	global_load_lds_dwordx4 v[204:205], off
	v_lshl_add_u64 v[204:205], v[210:211], 0, s[66:67]
	s_mov_b32 m0, s70
	s_nop 0
	global_load_lds_dwordx4 v[204:205], off
	s_waitcnt vmcnt(8)
	s_waitcnt lgkmcnt(0)
	s_setprio 1
	s_barrier
	v_mfma_f32_16x16x32_bf16 v[62:65], v[138:141], v[172:175], v[62:65]
	v_mfma_f32_16x16x32_bf16 v[58:61], v[148:151], v[172:175], v[58:61]
	v_mfma_f32_16x16x32_bf16 v[46:49], v[138:141], v[180:183], v[46:49]
	v_mfma_f32_16x16x32_bf16 v[42:45], v[148:151], v[180:183], v[42:45]
	v_mfma_f32_16x16x32_bf16 v[30:33], v[138:141], v[188:191], v[30:33]
	v_mfma_f32_16x16x32_bf16 v[26:29], v[148:151], v[188:191], v[26:29]
	v_mfma_f32_16x16x32_bf16 v[14:17], v[138:141], v[196:199], v[14:17]
	v_mfma_f32_16x16x32_bf16 v[10:13], v[148:151], v[196:199], v[10:13]
	v_mfma_f32_16x16x32_bf16 v[62:65], v[142:145], v[176:179], v[62:65]
	v_mfma_f32_16x16x32_bf16 v[58:61], v[152:155], v[176:179], v[58:61]
	v_mfma_f32_16x16x32_bf16 v[46:49], v[142:145], v[184:187], v[46:49]
	v_mfma_f32_16x16x32_bf16 v[42:45], v[152:155], v[184:187], v[42:45]
	v_mfma_f32_16x16x32_bf16 v[30:33], v[142:145], v[192:195], v[30:33]
	v_mfma_f32_16x16x32_bf16 v[26:29], v[152:155], v[192:195], v[26:29]
	v_mfma_f32_16x16x32_bf16 v[14:17], v[142:145], v[200:203], v[14:17]
	v_mfma_f32_16x16x32_bf16 v[10:13], v[152:155], v[200:203], v[10:13]
	s_setprio 0
	s_setprio 1
	v_mfma_f32_16x16x32_bf16 v[54:57], v[156:159], v[172:175], v[54:57]
	v_mfma_f32_16x16x32_bf16 v[50:53], v[164:167], v[172:175], v[50:53]
	v_mfma_f32_16x16x32_bf16 v[38:41], v[156:159], v[180:183], v[38:41]
	v_mfma_f32_16x16x32_bf16 v[34:37], v[164:167], v[180:183], v[34:37]
	v_mfma_f32_16x16x32_bf16 v[22:25], v[156:159], v[188:191], v[22:25]
	v_mfma_f32_16x16x32_bf16 v[18:21], v[164:167], v[188:191], v[18:21]
	v_mfma_f32_16x16x32_bf16 v[6:9], v[156:159], v[196:199], v[6:9]
	v_mfma_f32_16x16x32_bf16 v[2:5], v[164:167], v[196:199], v[2:5]
	v_mfma_f32_16x16x32_bf16 v[54:57], v[160:163], v[176:179], v[54:57]
	v_mfma_f32_16x16x32_bf16 v[50:53], v[168:171], v[176:179], v[50:53]
	v_mfma_f32_16x16x32_bf16 v[38:41], v[160:163], v[184:187], v[38:41]
	v_mfma_f32_16x16x32_bf16 v[34:37], v[168:171], v[184:187], v[34:37]
	v_mfma_f32_16x16x32_bf16 v[22:25], v[160:163], v[192:195], v[22:25]
	v_mfma_f32_16x16x32_bf16 v[18:21], v[168:171], v[192:195], v[18:21]
	v_mfma_f32_16x16x32_bf16 v[6:9], v[160:163], v[200:203], v[6:9]
	v_mfma_f32_16x16x32_bf16 v[2:5], v[168:171], v[200:203], v[2:5]
	s_barrier
	s_setprio 0
	s_add_i32 s39, s39, 2
	s_add_u32 s10, s10, 0x100
	s_addc_u32 s11, s11, 0
	s_add_u32 s29, s29, 0x100
	s_addc_u32 s38, s38, 0
	s_cmp_gt_u32 s39, 29
	s_cbranch_scc0 .LBB0_703
	s_and_b64 vcc, exec, s[18:19]
	s_cbranch_vccz .LBB0_706
	s_barrier

; #define PG8_STAGE(bufoff, gbase, voff) do { _Pragma("unroll") for (int _i = 0; _i < 2; ++_i) \
;         __builtin_amdgcn_global_load_lds((const unsigned*)((const char*)(gbase) + (voff)[_i]), (LAS unsigned*)(lds + (bufoff) + ldsw + _i * 8192), 16, 0, 0); } while (0)
; #define PG8_LDA(dst, b, h) do { _Pragma("unroll") for (int m = 0; m < NM; ++m) _Pragma("unroll") for (int k = 0; k < 2; ++k) dst[m][k] = *(const LAS bf16x8*)(lds + PG8_SA(b, h) + aoff + m * 2048 + k * 1024); } while (0)
; #define PG8_LDB(dst, b, h) do { _Pragma("unroll") for (int n = 0; n < 2; ++n) _Pragma("unroll") for (int k = 0; k < 2; ++k) dst[n][k] = *(const LAS bf16x8*)(lds + PG8_SB(b, h) + boff + n * 2048 + k * 1024); } while (0)
; #define PG8_MMA(ai, bj, At, Bt) do { __builtin_amdgcn_s_setprio(1); _Pragma("unroll") for (int m = 0; m < NM; ++m) _Pragma("unroll") for (int n = 0; n < 2; ++n) _Pragma("unroll") for (int k = 0; k < 2; ++k) \
;         acc[ai][bj][m][n] = __builtin_amdgcn_mfma_f32_16x16x32_bf16(Bt[n][k], At[m][k], acc[ai][bj][m][n], 0, 0, 0); __builtin_amdgcn_s_setprio(0); } while (0)
; #define PG8_WAIT_V(n) asm volatile("s_waitcnt vmcnt(" #n ")" ::: "memory")
; #define PG8_WAIT_L(n) asm volatile("s_waitcnt lgkmcnt(" #n ")" ::: "memory")
; #define PG8_BAR __builtin_amdgcn_s_barrier()
; #define PG8_SCHED __builtin_amdgcn_sched_barrier(0)
;     ...
;             const bool last = (t == nt - 2);
;             const char* a1 = cA + (size_t)(t + 1) * kstep;
;             const char* a2 = last ? nA : cA + (size_t)(t + 2) * kstep; const char* b2 = last ? nB : cB + (size_t)(t + 2) * kstep;
;             const char* a3 = a2 + kstep; const char* b3 = b2 + kstep;
;             if constexpr (SP2) {
;             PG8_LDB(B0, 0, 0); PG8_LDB(B1, 0, 1); PG8_SCHED; PG8_LDA(At, 0, 0); PG8_STAGE(PG8_SA(1, 1), a1 + hstepA, voffA);
;             PG8_WAIT_V(8); PG8_WAIT_L(0); PG8_BAR; PG8_MMA(0, 0, At, B0); PG8_MMA(0, 1, At, B1); PG8_BAR; PG8_SCHED;
;             PG8_LDA(At, 0, 1); PG8_STAGE(PG8_SB(0, 0), b2, voffB); PG8_STAGE(PG8_SB(0, 1), b2 + hstepB, voffB); PG8_STAGE(PG8_SA(0, 0), a2, voffA);
;             PG8_WAIT_V(8); PG8_WAIT_L(0); PG8_BAR; PG8_MMA(1, 0, At, B0); PG8_MMA(1, 1, At, B1); PG8_BAR; PG8_SCHED;
.LBB0_1192:
	v_add_u32_e32 v0, s49, v216
	ds_read_b128 v[10:13], v0
	ds_read_b128 v[14:17], v0 offset:1024
	ds_read_b128 v[18:21], v0 offset:2048
	ds_read_b128 v[22:25], v0 offset:3072
	v_add_u32_e32 v0, s58, v216
	ds_read_b128 v[26:29], v0
	ds_read_b128 v[30:33], v0 offset:1024
	ds_read_b128 v[42:45], v0 offset:2048
	ds_read_b128 v[46:49], v0 offset:3072
	s_add_u32 s12, s10, 0xfffe0080
	s_addc_u32 s13, s11, -1
	s_cmp_eq_u32 s54, 4
	s_cselect_b32 s35, s2, s13
	s_cselect_b32 s34, s3, s12
	s_cselect_b32 s13, s7, s52
	s_cselect_b32 s12, s27, s9
	s_add_i32 m0, s62, 0xc000
	ds_read_b128 v[50:53], v217
	ds_read_b128 v[54:57], v217 offset:1024
	ds_read_b128 v[58:61], v217 offset:2048
	ds_read_b128 v[62:65], v217 offset:3072
	ds_read_b128 v[178:181], v217 offset:4096
	ds_read_b128 v[182:185], v217 offset:5120
	ds_read_b128 v[198:201], v217 offset:6144
	ds_read_b128 v[208:211], v217 offset:7168
	global_load_lds_dwordx4 v194, s[10:11]
	s_add_i32 m0, s62, 0xe000
	s_nop 0
	global_load_lds_dwordx4 v196, s[10:11]
	s_waitcnt vmcnt(8)
	s_waitcnt lgkmcnt(0)
	s_setprio 1
	s_barrier
	v_mfma_f32_16x16x32_bf16 v[38:41], v[10:13], v[50:53], v[38:41]
	v_mfma_f32_16x16x32_bf16 v[34:37], v[18:21], v[50:53], v[34:37]
	v_mfma_f32_16x16x32_bf16 v[174:177], v[10:13], v[58:61], v[174:177]
	v_mfma_f32_16x16x32_bf16 v[170:173], v[18:21], v[58:61], v[170:173]
	v_mfma_f32_16x16x32_bf16 v[158:161], v[10:13], v[178:181], v[158:161]
	v_mfma_f32_16x16x32_bf16 v[154:157], v[18:21], v[178:181], v[154:157]
	v_mfma_f32_16x16x32_bf16 v[142:145], v[10:13], v[198:201], v[142:145]
	v_mfma_f32_16x16x32_bf16 v[138:141], v[18:21], v[198:201], v[138:141]
	v_mfma_f32_16x16x32_bf16 v[38:41], v[14:17], v[54:57], v[38:41]
	v_mfma_f32_16x16x32_bf16 v[34:37], v[22:25], v[54:57], v[34:37]
	v_mfma_f32_16x16x32_bf16 v[174:177], v[14:17], v[62:65], v[174:177]
	v_mfma_f32_16x16x32_bf16 v[170:173], v[22:25], v[62:65], v[170:173]
	v_mfma_f32_16x16x32_bf16 v[158:161], v[14:17], v[182:185], v[158:161]
	v_mfma_f32_16x16x32_bf16 v[154:157], v[22:25], v[182:185], v[154:157]
	v_mfma_f32_16x16x32_bf16 v[142:145], v[14:17], v[208:211], v[142:145]
	v_mfma_f32_16x16x32_bf16 v[138:141], v[22:25], v[208:211], v[138:141]
	s_setprio 0
	s_setprio 1
	v_mfma_f32_16x16x32_bf16 v[6:9], v[26:29], v[50:53], v[6:9]
	v_mfma_f32_16x16x32_bf16 v[2:5], v[42:45], v[50:53], v[2:5]
	v_mfma_f32_16x16x32_bf16 v[6:9], v[30:33], v[54:57], v[6:9]
	v_mfma_f32_16x16x32_bf16 v[2:5], v[46:49], v[54:57], v[2:5]
	v_mfma_f32_16x16x32_bf16 v[50:53], v[26:29], v[58:61], v[166:169]
	v_mfma_f32_16x16x32_bf16 v[54:57], v[42:45], v[58:61], v[162:165]
	v_mfma_f32_16x16x32_bf16 v[134:137], v[26:29], v[198:201], v[134:137]
	v_mfma_f32_16x16x32_bf16 v[130:133], v[42:45], v[198:201], v[130:133]
	v_mfma_f32_16x16x32_bf16 v[50:53], v[30:33], v[62:65], v[50:53]
	v_mfma_f32_16x16x32_bf16 v[54:57], v[46:49], v[62:65], v[54:57]
	v_mfma_f32_16x16x32_bf16 v[58:61], v[26:29], v[178:181], v[150:153]
	v_mfma_f32_16x16x32_bf16 v[62:65], v[42:45], v[178:181], v[146:149]
	v_mfma_f32_16x16x32_bf16 v[134:137], v[30:33], v[208:211], v[134:137]
	v_mfma_f32_16x16x32_bf16 v[130:133], v[46:49], v[208:211], v[130:133]
	v_mfma_f32_16x16x32_bf16 v[58:61], v[30:33], v[182:185], v[58:61]
	v_mfma_f32_16x16x32_bf16 v[62:65], v[46:49], v[182:185], v[62:65]
	s_barrier
	s_setprio 0
	s_mov_b32 m0, s50
	v_lshl_add_u64 v[202:203], s[12:13], 0, v[188:189]
	s_add_u32 s56, s12, 0x20000
	ds_read_b128 v[146:149], v217 offset:16384
	ds_read_b128 v[150:153], v217 offset:17408
	ds_read_b128 v[162:165], v217 offset:18432
	ds_read_b128 v[166:169], v217 offset:19456
	ds_read_b128 v[178:181], v217 offset:20480
	ds_read_b128 v[182:185], v217 offset:21504
	ds_read_b128 v[198:201], v217 offset:22528
	ds_read_b128 v[208:211], v217 offset:23552
	global_load_lds_dwordx4 v188, s[12:13]
	v_lshl_add_u64 v[204:205], s[12:13], 0, v[192:193]
	s_mov_b32 m0, s51
	s_addc_u32 s57, s13, 0
	global_load_lds_dwordx4 v192, s[12:13]
	s_mov_b32 m0, s59
	v_lshl_add_u64 v[222:223], s[34:35], 0, v[190:191]
	global_load_lds_dwordx4 v188, s[56:57]
	s_mov_b32 m0, s60
	s_nop 0
	global_load_lds_dwordx4 v192, s[56:57]
	v_lshl_add_u64 v[206:207], s[34:35], 0, v[186:187]
	s_mov_b32 m0, s62
	s_nop 0
	global_load_lds_dwordx4 v186, s[34:35]
	s_mov_b32 m0, s63
	s_nop 0
	global_load_lds_dwordx4 v190, s[34:35]
	s_waitcnt vmcnt(8)
	s_waitcnt lgkmcnt(0)
	s_setprio 1
	s_barrier
	v_mfma_f32_16x16x32_bf16 v[126:129], v[10:13], v[146:149], v[126:129]
	v_mfma_f32_16x16x32_bf16 v[122:125], v[18:21], v[146:149], v[122:125]
	v_mfma_f32_16x16x32_bf16 v[110:113], v[10:13], v[162:165], v[110:113]
	v_mfma_f32_16x16x32_bf16 v[106:109], v[18:21], v[162:165], v[106:109]
	v_mfma_f32_16x16x32_bf16 v[94:97], v[10:13], v[178:181], v[94:97]
	v_mfma_f32_16x16x32_bf16 v[90:93], v[18:21], v[178:181], v[90:93]
	v_mfma_f32_16x16x32_bf16 v[10:13], v[10:13], v[198:201], v[78:81]
	v_mfma_f32_16x16x32_bf16 v[126:129], v[14:17], v[150:153], v[126:129]
	v_mfma_f32_16x16x32_bf16 v[122:125], v[22:25], v[150:153], v[122:125]
	v_mfma_f32_16x16x32_bf16 v[110:113], v[14:17], v[166:169], v[110:113]
	v_mfma_f32_16x16x32_bf16 v[106:109], v[22:25], v[166:169], v[106:109]
	v_mfma_f32_16x16x32_bf16 v[94:97], v[14:17], v[182:185], v[94:97]
	v_mfma_f32_16x16x32_bf16 v[90:93], v[22:25], v[182:185], v[90:93]
	v_mfma_f32_16x16x32_bf16 v[10:13], v[14:17], v[208:211], v[10:13]
	v_mfma_f32_16x16x32_bf16 v[14:17], v[18:21], v[198:201], v[74:77]
	v_mfma_f32_16x16x32_bf16 v[14:17], v[22:25], v[208:211], v[14:17]
	s_setprio 0
	s_setprio 1
	v_mfma_f32_16x16x32_bf16 v[74:77], v[26:29], v[162:165], v[102:105]
	v_mfma_f32_16x16x32_bf16 v[102:105], v[30:33], v[166:169], v[74:77]
	v_mfma_f32_16x16x32_bf16 v[74:77], v[42:45], v[162:165], v[98:101]
	v_mfma_f32_16x16x32_bf16 v[98:101], v[46:49], v[166:169], v[74:77]
	v_mfma_f32_16x16x32_bf16 v[74:77], v[26:29], v[178:181], v[86:89]
	v_mfma_f32_16x16x32_bf16 v[18:21], v[26:29], v[146:149], v[118:121]
	v_mfma_f32_16x16x32_bf16 v[86:89], v[30:33], v[182:185], v[74:77]
	v_mfma_f32_16x16x32_bf16 v[74:77], v[42:45], v[178:181], v[82:85]
	v_mfma_f32_16x16x32_bf16 v[26:29], v[26:29], v[198:201], v[70:73]
	v_mfma_f32_16x16x32_bf16 v[18:21], v[30:33], v[150:153], v[18:21]
	v_mfma_f32_16x16x32_bf16 v[22:25], v[42:45], v[146:149], v[114:117]
	v_mfma_f32_16x16x32_bf16 v[82:85], v[46:49], v[182:185], v[74:77]
	v_mfma_f32_16x16x32_bf16 v[26:29], v[30:33], v[208:211], v[26:29]
	v_mfma_f32_16x16x32_bf16 v[30:33], v[42:45], v[198:201], v[66:69]
	v_mfma_f32_16x16x32_bf16 v[22:25], v[46:49], v[150:153], v[22:25]
	v_mfma_f32_16x16x32_bf16 v[30:33], v[46:49], v[208:211], v[30:33]
	s_barrier
; #define PG8_STAGE(bufoff, gbase, voff) do { _Pragma("unroll") for (int _i = 0; _i < 2; ++_i) \
;         __builtin_amdgcn_global_load_lds((const unsigned*)((const char*)(gbase) + (voff)[_i]), (LAS unsigned*)(lds + (bufoff) + ldsw + _i * 8192), 16, 0, 0); } while (0)
; #define PG8_LDA(dst, b, h) do { _Pragma("unroll") for (int m = 0; m < NM; ++m) _Pragma("unroll") for (int k = 0; k < 2; ++k) dst[m][k] = *(const LAS bf16x8*)(lds + PG8_SA(b, h) + aoff + m * 2048 + k * 1024); } while (0)
; #define PG8_LDB(dst, b, h) do { _Pragma("unroll") for (int n = 0; n < 2; ++n) _Pragma("unroll") for (int k = 0; k < 2; ++k) dst[n][k] = *(const LAS bf16x8*)(lds + PG8_SB(b, h) + boff + n * 2048 + k * 1024); } while (0)
; #define PG8_MMA(ai, bj, At, Bt) do { __builtin_amdgcn_s_setprio(1); _Pragma("unroll") for (int m = 0; m < NM; ++m) _Pragma("unroll") for (int n = 0; n < 2; ++n) _Pragma("unroll") for (int k = 0; k < 2; ++k) \
;         acc[ai][bj][m][n] = __builtin_amdgcn_mfma_f32_16x16x32_bf16(Bt[n][k], At[m][k], acc[ai][bj][m][n], 0, 0, 0); __builtin_amdgcn_s_setprio(0); } while (0)
; #define PG8_WAIT_V(n) asm volatile("s_waitcnt vmcnt(" #n ")" ::: "memory")
; #define PG8_WAIT_L(n) asm volatile("s_waitcnt lgkmcnt(" #n ")" ::: "memory")
; #define PG8_BAR __builtin_amdgcn_s_barrier()
; #define PG8_SCHED __builtin_amdgcn_sched_barrier(0)
;     ...
;             PG8_LDB(B0, 1, 0); PG8_LDB(B1, 1, 1); PG8_SCHED; PG8_LDA(At, 1, 0); PG8_STAGE(PG8_SA(0, 1), a2 + hstepA, voffA);
;             PG8_WAIT_V(8); PG8_WAIT_L(0); PG8_BAR; PG8_MMA(0, 0, At, B0); PG8_MMA(0, 1, At, B1); PG8_BAR; PG8_SCHED;
;             PG8_LDA(At, 1, 1); PG8_STAGE(PG8_SB(1, 0), b3, voffB); PG8_STAGE(PG8_SB(1, 1), b3 + hstepB, voffB); PG8_STAGE(PG8_SA(1, 0), a3, voffA);
;             PG8_WAIT_V(8); PG8_WAIT_L(0); PG8_BAR; PG8_MMA(1, 0, At, B0); PG8_MMA(1, 1, At, B1); PG8_BAR; PG8_SCHED;
	s_setprio 0
	v_add_u32_e32 v0, s69, v216
	ds_read_b128 v[42:45], v0
	ds_read_b128 v[46:49], v0 offset:1024
	ds_read_b128 v[66:69], v0 offset:2048
	ds_read_b128 v[70:73], v0 offset:3072
	v_add_u32_e32 v0, s74, v216
	ds_read_b128 v[178:181], v0
	ds_read_b128 v[182:185], v0 offset:1024
	ds_read_b128 v[198:201], v0 offset:2048
	ds_read_b128 v[208:211], v0 offset:3072
	s_add_u32 s34, s34, 0x20000
	s_addc_u32 s35, s35, 0
	s_mov_b32 m0, s64
	ds_read_b128 v[74:77], v217 offset:32768
	ds_read_b128 v[78:81], v217 offset:33792
	ds_read_b128 v[114:117], v217 offset:34816
	ds_read_b128 v[118:121], v217 offset:35840
	ds_read_b128 v[146:149], v217 offset:36864
	ds_read_b128 v[212:215], v217 offset:37888
	ds_read_b128 v[218:221], v217 offset:38912
	ds_read_b128 v[226:229], v217 offset:39936
	global_load_lds_dwordx4 v186, s[34:35]
	s_mov_b32 m0, s68
	s_nop 0
	global_load_lds_dwordx4 v190, s[34:35]
	s_waitcnt vmcnt(8)
	s_waitcnt lgkmcnt(0)
	s_setprio 1
	s_barrier
	v_mfma_f32_16x16x32_bf16 v[150:153], v[42:45], v[114:117], v[174:177]
	v_mfma_f32_16x16x32_bf16 v[174:177], v[46:49], v[118:121], v[150:153]
	v_mfma_f32_16x16x32_bf16 v[150:153], v[66:69], v[114:117], v[170:173]
	v_mfma_f32_16x16x32_bf16 v[170:173], v[70:73], v[118:121], v[150:153]
	v_mfma_f32_16x16x32_bf16 v[150:153], v[42:45], v[146:149], v[158:161]
	v_mfma_f32_16x16x32_bf16 v[38:41], v[42:45], v[74:77], v[38:41]
	v_mfma_f32_16x16x32_bf16 v[34:37], v[66:69], v[74:77], v[34:37]
	v_mfma_f32_16x16x32_bf16 v[158:161], v[46:49], v[212:215], v[150:153]
	v_mfma_f32_16x16x32_bf16 v[150:153], v[66:69], v[146:149], v[154:157]
	v_mfma_f32_16x16x32_bf16 v[142:145], v[42:45], v[218:221], v[142:145]
	v_mfma_f32_16x16x32_bf16 v[138:141], v[66:69], v[218:221], v[138:141]
	v_mfma_f32_16x16x32_bf16 v[38:41], v[46:49], v[78:81], v[38:41]
	v_mfma_f32_16x16x32_bf16 v[34:37], v[70:73], v[78:81], v[34:37]
	v_mfma_f32_16x16x32_bf16 v[154:157], v[70:73], v[212:215], v[150:153]
	v_mfma_f32_16x16x32_bf16 v[142:145], v[46:49], v[226:229], v[142:145]
	v_mfma_f32_16x16x32_bf16 v[138:141], v[70:73], v[226:229], v[138:141]
	s_setprio 0
	s_setprio 1
	v_mfma_f32_16x16x32_bf16 v[50:53], v[178:181], v[114:117], v[50:53]
	v_mfma_f32_16x16x32_bf16 v[166:169], v[182:185], v[118:121], v[50:53]
	v_mfma_f32_16x16x32_bf16 v[50:53], v[198:201], v[114:117], v[54:57]
	v_mfma_f32_16x16x32_bf16 v[162:165], v[208:211], v[118:121], v[50:53]
	v_mfma_f32_16x16x32_bf16 v[50:53], v[178:181], v[146:149], v[58:61]
	v_mfma_f32_16x16x32_bf16 v[150:153], v[182:185], v[212:215], v[50:53]
	v_mfma_f32_16x16x32_bf16 v[50:53], v[198:201], v[146:149], v[62:65]
	v_mfma_f32_16x16x32_bf16 v[146:149], v[208:211], v[212:215], v[50:53]
	v_mfma_f32_16x16x32_bf16 v[50:53], v[178:181], v[218:221], v[134:137]
	v_mfma_f32_16x16x32_bf16 v[6:9], v[178:181], v[74:77], v[6:9]
	v_mfma_f32_16x16x32_bf16 v[2:5], v[198:201], v[74:77], v[2:5]
	v_mfma_f32_16x16x32_bf16 v[134:137], v[182:185], v[226:229], v[50:53]
	v_mfma_f32_16x16x32_bf16 v[50:53], v[198:201], v[218:221], v[130:133]
	v_mfma_f32_16x16x32_bf16 v[6:9], v[182:185], v[78:81], v[6:9]
	v_mfma_f32_16x16x32_bf16 v[2:5], v[208:211], v[78:81], v[2:5]
	v_mfma_f32_16x16x32_bf16 v[130:133], v[208:211], v[226:229], v[50:53]
	s_barrier
	s_setprio 0
	s_mov_b32 m0, s70
	v_lshl_add_u64 v[74:75], v[202:203], 0, s[66:67]
	s_add_u32 s12, s12, 0x20080
	ds_read_b128 v[50:53], v217 offset:49152
	ds_read_b128 v[54:57], v217 offset:50176
	ds_read_b128 v[58:61], v217 offset:51200
	ds_read_b128 v[62:65], v217 offset:52224
	ds_read_b128 v[212:215], v217 offset:53248
	ds_read_b128 v[218:221], v217 offset:54272
	ds_read_b128 v[226:229], v217 offset:55296
	ds_read_b128 v[230:233], v217 offset:56320
	global_load_lds_dwordx4 v[74:75], off
	v_lshl_add_u64 v[74:75], v[204:205], 0, s[66:67]
	s_mov_b32 m0, s71
	s_addc_u32 s13, s13, 0
	global_load_lds_dwordx4 v[74:75], off
	s_mov_b32 m0, s75
	s_nop 0
	global_load_lds_dwordx4 v188, s[12:13]
	s_mov_b32 m0, s80
	s_nop 0
	global_load_lds_dwordx4 v192, s[12:13]
	v_lshl_add_u64 v[74:75], v[206:207], 0, s[66:67]
	s_mov_b32 m0, s72
	s_nop 0
	global_load_lds_dwordx4 v[74:75], off
	v_lshl_add_u64 v[74:75], v[222:223], 0, s[66:67]
	s_mov_b32 m0, s73
	s_nop 0
	global_load_lds_dwordx4 v[74:75], off
	s_waitcnt vmcnt(8)
	s_waitcnt lgkmcnt(0)
	s_setprio 1
	s_barrier
	v_mfma_f32_16x16x32_bf16 v[74:77], v[42:45], v[50:53], v[126:129]
	v_mfma_f32_16x16x32_bf16 v[126:129], v[46:49], v[54:57], v[74:77]
	v_mfma_f32_16x16x32_bf16 v[74:77], v[66:69], v[50:53], v[122:125]
	v_mfma_f32_16x16x32_bf16 v[122:125], v[70:73], v[54:57], v[74:77]
	v_mfma_f32_16x16x32_bf16 v[74:77], v[42:45], v[58:61], v[110:113]
	v_mfma_f32_16x16x32_bf16 v[110:113], v[46:49], v[62:65], v[74:77]
	v_mfma_f32_16x16x32_bf16 v[74:77], v[66:69], v[58:61], v[106:109]
	v_mfma_f32_16x16x32_bf16 v[106:109], v[70:73], v[62:65], v[74:77]
	v_mfma_f32_16x16x32_bf16 v[74:77], v[42:45], v[212:215], v[94:97]
	v_mfma_f32_16x16x32_bf16 v[10:13], v[42:45], v[226:229], v[10:13]
	v_mfma_f32_16x16x32_bf16 v[94:97], v[46:49], v[218:221], v[74:77]
	v_mfma_f32_16x16x32_bf16 v[74:77], v[66:69], v[212:215], v[90:93]
	v_mfma_f32_16x16x32_bf16 v[78:81], v[46:49], v[230:233], v[10:13]
	v_mfma_f32_16x16x32_bf16 v[10:13], v[66:69], v[226:229], v[14:17]
	v_mfma_f32_16x16x32_bf16 v[90:93], v[70:73], v[218:221], v[74:77]
	v_mfma_f32_16x16x32_bf16 v[74:77], v[70:73], v[230:233], v[10:13]
	s_setprio 0
	s_setprio 1
	v_mfma_f32_16x16x32_bf16 v[10:13], v[178:181], v[50:53], v[18:21]
	v_mfma_f32_16x16x32_bf16 v[118:121], v[182:185], v[54:57], v[10:13]
	v_mfma_f32_16x16x32_bf16 v[10:13], v[198:201], v[50:53], v[22:25]
	v_mfma_f32_16x16x32_bf16 v[114:117], v[208:211], v[54:57], v[10:13]
	v_mfma_f32_16x16x32_bf16 v[10:13], v[178:181], v[58:61], v[102:105]
	v_mfma_f32_16x16x32_bf16 v[102:105], v[182:185], v[62:65], v[10:13]
	v_mfma_f32_16x16x32_bf16 v[10:13], v[198:201], v[58:61], v[98:101]
	v_mfma_f32_16x16x32_bf16 v[98:101], v[208:211], v[62:65], v[10:13]
	v_mfma_f32_16x16x32_bf16 v[10:13], v[178:181], v[212:215], v[86:89]
	v_mfma_f32_16x16x32_bf16 v[86:89], v[182:185], v[218:221], v[10:13]
	v_mfma_f32_16x16x32_bf16 v[10:13], v[198:201], v[212:215], v[82:85]
	v_mfma_f32_16x16x32_bf16 v[82:85], v[208:211], v[218:221], v[10:13]
	v_mfma_f32_16x16x32_bf16 v[10:13], v[178:181], v[226:229], v[26:29]
	v_mfma_f32_16x16x32_bf16 v[70:73], v[182:185], v[230:233], v[10:13]
	v_mfma_f32_16x16x32_bf16 v[10:13], v[198:201], v[226:229], v[30:33]
	v_mfma_f32_16x16x32_bf16 v[66:69], v[208:211], v[230:233], v[10:13]
	s_barrier
	s_setprio 0
	s_add_i32 s54, s54, 2
	s_add_u32 s10, s10, 0x100
	s_addc_u32 s11, s11, 0
	s_add_u32 s9, s9, 0x100
	s_addc_u32 s52, s52, 0
	s_cmp_gt_u32 s54, 5
	s_cbranch_scc0 .LBB0_1192
	s_and_b64 vcc, exec, s[16:17]
	s_cbranch_vccz .LBB0_1195
	s_barrier

; #define PG8_STAGE(bufoff, gbase, voff) do { _Pragma("unroll") for (int _i = 0; _i < 2; ++_i) \
;         __builtin_amdgcn_global_load_lds((const unsigned*)((const char*)(gbase) + (voff)[_i]), (LAS unsigned*)(lds + (bufoff) + ldsw + _i * 8192), 16, 0, 0); } while (0)
; #define PG8_LDA(dst, b, h) do { _Pragma("unroll") for (int m = 0; m < NM; ++m) _Pragma("unroll") for (int k = 0; k < 2; ++k) dst[m][k] = *(const LAS bf16x8*)(lds + PG8_SA(b, h) + aoff + m * 2048 + k * 1024); } while (0)
; #define PG8_LDB(dst, b, h) do { _Pragma("unroll") for (int n = 0; n < 2; ++n) _Pragma("unroll") for (int k = 0; k < 2; ++k) dst[n][k] = *(const LAS bf16x8*)(lds + PG8_SB(b, h) + boff + n * 2048 + k * 1024); } while (0)
; #define PG8_MMA(ai, bj, At, Bt) do { __builtin_amdgcn_s_setprio(1); _Pragma("unroll") for (int m = 0; m < NM; ++m) _Pragma("unroll") for (int n = 0; n < 2; ++n) _Pragma("unroll") for (int k = 0; k < 2; ++k) \
;         acc[ai][bj][m][n] = __builtin_amdgcn_mfma_f32_16x16x32_bf16(Bt[n][k], At[m][k], acc[ai][bj][m][n], 0, 0, 0); __builtin_amdgcn_s_setprio(0); } while (0)
; #define PG8_WAIT_V(n) asm volatile("s_waitcnt vmcnt(" #n ")" ::: "memory")
; #define PG8_WAIT_L(n) asm volatile("s_waitcnt lgkmcnt(" #n ")" ::: "memory")
; #define PG8_BAR __builtin_amdgcn_s_barrier()
; #define PG8_SCHED __builtin_amdgcn_sched_barrier(0)
;     ...
;             const bool last = (t == nt - 2);
;             const char* a1 = cA + (size_t)(t + 1) * kstep;
;             const char* a2 = last ? nA : cA + (size_t)(t + 2) * kstep; const char* b2 = last ? nB : cB + (size_t)(t + 2) * kstep;
;             const char* a3 = a2 + kstep; const char* b3 = b2 + kstep;
;             if constexpr (SP2) {
;             PG8_LDB(B0, 0, 0); PG8_LDB(B1, 0, 1); PG8_SCHED; PG8_LDA(At, 0, 0); PG8_STAGE(PG8_SA(1, 1), a1 + hstepA, voffA);
;             PG8_WAIT_V(8); PG8_WAIT_L(0); PG8_BAR; PG8_MMA(0, 0, At, B0); PG8_MMA(0, 1, At, B1); PG8_BAR; PG8_SCHED;
;             PG8_LDA(At, 0, 1); PG8_STAGE(PG8_SB(0, 0), b2, voffB); PG8_STAGE(PG8_SB(0, 1), b2 + hstepB, voffB); PG8_STAGE(PG8_SA(0, 0), a2, voffA);
;             PG8_WAIT_V(8); PG8_WAIT_L(0); PG8_BAR; PG8_MMA(1, 0, At, B0); PG8_MMA(1, 1, At, B1); PG8_BAR; PG8_SCHED;
.LBB0_1454:
	v_add_u32_e32 v140, s31, v142
	ds_read_b128 v[144:147], v140
	ds_read_b128 v[148:151], v140 offset:1024
	ds_read_b128 v[152:155], v140 offset:2048
	ds_read_b128 v[156:159], v140 offset:3072
	v_add_u32_e32 v140, s35, v142
	ds_read_b128 v[160:163], v140
	ds_read_b128 v[164:167], v140 offset:1024
	ds_read_b128 v[168:171], v140 offset:2048
	ds_read_b128 v[172:175], v140 offset:3072
	s_add_u32 s6, s20, 0x100
	s_addc_u32 s7, s21, 0
	s_cmp_eq_u32 s73, 4
	s_cselect_b32 s25, s17, s7
	s_cselect_b32 s24, s16, s6
	s_cselect_b32 s23, s2, s60
	s_cselect_b32 s22, s3, s15
	s_add_i32 m0, s45, 0xc000
	ds_read_b128 v[176:179], v143
	ds_read_b128 v[180:183], v143 offset:1024
	ds_read_b128 v[184:187], v143 offset:2048
	ds_read_b128 v[188:191], v143 offset:3072
	ds_read_b128 v[192:195], v143 offset:4096
	ds_read_b128 v[196:199], v143 offset:5120
	ds_read_b128 v[200:203], v143 offset:6144
	ds_read_b128 v[208:211], v143 offset:7168
	global_load_lds_dwordx4 v136, s[20:21]
	s_add_i32 m0, s45, 0xe000
	s_nop 0
	global_load_lds_dwordx4 v138, s[20:21]
	s_waitcnt vmcnt(8)
	s_waitcnt lgkmcnt(0)
	s_setprio 1
	s_barrier
	v_mfma_f32_16x16x32_bf16 v[126:129], v[144:147], v[176:179], v[126:129]
	v_mfma_f32_16x16x32_bf16 v[122:125], v[152:155], v[176:179], v[122:125]
	v_mfma_f32_16x16x32_bf16 v[118:121], v[144:147], v[184:187], v[118:121]
	v_mfma_f32_16x16x32_bf16 v[114:117], v[152:155], v[184:187], v[114:117]
	v_mfma_f32_16x16x32_bf16 v[110:113], v[144:147], v[192:195], v[110:113]
	v_mfma_f32_16x16x32_bf16 v[106:109], v[152:155], v[192:195], v[106:109]
	v_mfma_f32_16x16x32_bf16 v[102:105], v[144:147], v[200:203], v[102:105]
	v_mfma_f32_16x16x32_bf16 v[98:101], v[152:155], v[200:203], v[98:101]
	v_mfma_f32_16x16x32_bf16 v[126:129], v[148:151], v[180:183], v[126:129]
	v_mfma_f32_16x16x32_bf16 v[122:125], v[156:159], v[180:183], v[122:125]
	v_mfma_f32_16x16x32_bf16 v[118:121], v[148:151], v[188:191], v[118:121]
	v_mfma_f32_16x16x32_bf16 v[114:117], v[156:159], v[188:191], v[114:117]
	v_mfma_f32_16x16x32_bf16 v[110:113], v[148:151], v[196:199], v[110:113]
	v_mfma_f32_16x16x32_bf16 v[106:109], v[156:159], v[196:199], v[106:109]
	v_mfma_f32_16x16x32_bf16 v[102:105], v[148:151], v[208:211], v[102:105]
	v_mfma_f32_16x16x32_bf16 v[98:101], v[156:159], v[208:211], v[98:101]
	s_setprio 0
	s_setprio 1
	v_mfma_f32_16x16x32_bf16 v[62:65], v[160:163], v[176:179], v[62:65]
	v_mfma_f32_16x16x32_bf16 v[58:61], v[168:171], v[176:179], v[58:61]
	v_mfma_f32_16x16x32_bf16 v[54:57], v[160:163], v[184:187], v[54:57]
	v_mfma_f32_16x16x32_bf16 v[50:53], v[168:171], v[184:187], v[50:53]
	v_mfma_f32_16x16x32_bf16 v[46:49], v[160:163], v[192:195], v[46:49]
	v_mfma_f32_16x16x32_bf16 v[42:45], v[168:171], v[192:195], v[42:45]
	v_mfma_f32_16x16x32_bf16 v[38:41], v[160:163], v[200:203], v[38:41]
	v_mfma_f32_16x16x32_bf16 v[34:37], v[168:171], v[200:203], v[34:37]
	v_mfma_f32_16x16x32_bf16 v[62:65], v[164:167], v[180:183], v[62:65]
	v_mfma_f32_16x16x32_bf16 v[58:61], v[172:175], v[180:183], v[58:61]
	v_mfma_f32_16x16x32_bf16 v[54:57], v[164:167], v[188:191], v[54:57]
	v_mfma_f32_16x16x32_bf16 v[50:53], v[172:175], v[188:191], v[50:53]
	v_mfma_f32_16x16x32_bf16 v[46:49], v[164:167], v[196:199], v[46:49]
	v_mfma_f32_16x16x32_bf16 v[42:45], v[172:175], v[196:199], v[42:45]
	v_mfma_f32_16x16x32_bf16 v[38:41], v[164:167], v[208:211], v[38:41]
	v_mfma_f32_16x16x32_bf16 v[34:37], v[172:175], v[208:211], v[34:37]
	s_barrier
	s_setprio 0
	s_mov_b32 m0, s33
	v_lshl_add_u64 v[140:141], s[22:23], 0, v[0:1]
	s_add_u32 s20, s22, 0x20000
	ds_read_b128 v[176:179], v143 offset:16384
	ds_read_b128 v[180:183], v143 offset:17408
	ds_read_b128 v[184:187], v143 offset:18432
	ds_read_b128 v[188:191], v143 offset:19456
	ds_read_b128 v[192:195], v143 offset:20480
	ds_read_b128 v[196:199], v143 offset:21504
	ds_read_b128 v[200:203], v143 offset:22528
	ds_read_b128 v[208:211], v143 offset:23552
	global_load_lds_dwordx4 v0, s[22:23]
	v_lshl_add_u64 v[204:205], s[22:23], 0, v[134:135]
	s_mov_b32 m0, s34
	s_addc_u32 s21, s23, 0
	global_load_lds_dwordx4 v134, s[22:23]
	s_mov_b32 m0, s43
	v_lshl_add_u64 v[212:213], s[24:25], 0, v[132:133]
	global_load_lds_dwordx4 v0, s[20:21]
	s_mov_b32 m0, s44
	s_nop 0
	global_load_lds_dwordx4 v134, s[20:21]
	v_lshl_add_u64 v[206:207], s[24:25], 0, v[130:131]
	s_mov_b32 m0, s45
	s_nop 0
	global_load_lds_dwordx4 v130, s[24:25]
	s_mov_b32 m0, s47
	s_nop 0
	global_load_lds_dwordx4 v132, s[24:25]
	s_waitcnt vmcnt(8)
	s_waitcnt lgkmcnt(0)
	s_setprio 1
	s_barrier
	v_mfma_f32_16x16x32_bf16 v[94:97], v[144:147], v[176:179], v[94:97]
	v_mfma_f32_16x16x32_bf16 v[90:93], v[152:155], v[176:179], v[90:93]
	v_mfma_f32_16x16x32_bf16 v[86:89], v[144:147], v[184:187], v[86:89]
	v_mfma_f32_16x16x32_bf16 v[82:85], v[152:155], v[184:187], v[82:85]
	v_mfma_f32_16x16x32_bf16 v[78:81], v[144:147], v[192:195], v[78:81]
	v_mfma_f32_16x16x32_bf16 v[74:77], v[152:155], v[192:195], v[74:77]
	v_mfma_f32_16x16x32_bf16 v[70:73], v[144:147], v[200:203], v[70:73]
	v_mfma_f32_16x16x32_bf16 v[66:69], v[152:155], v[200:203], v[66:69]
	v_mfma_f32_16x16x32_bf16 v[94:97], v[148:151], v[180:183], v[94:97]
	v_mfma_f32_16x16x32_bf16 v[90:93], v[156:159], v[180:183], v[90:93]
	v_mfma_f32_16x16x32_bf16 v[86:89], v[148:151], v[188:191], v[86:89]
	v_mfma_f32_16x16x32_bf16 v[82:85], v[156:159], v[188:191], v[82:85]
	v_mfma_f32_16x16x32_bf16 v[78:81], v[148:151], v[196:199], v[78:81]
	v_mfma_f32_16x16x32_bf16 v[74:77], v[156:159], v[196:199], v[74:77]
	v_mfma_f32_16x16x32_bf16 v[70:73], v[148:151], v[208:211], v[70:73]
	v_mfma_f32_16x16x32_bf16 v[66:69], v[156:159], v[208:211], v[66:69]
	s_setprio 0
	s_setprio 1
	v_mfma_f32_16x16x32_bf16 v[30:33], v[160:163], v[176:179], v[30:33]
	v_mfma_f32_16x16x32_bf16 v[26:29], v[168:171], v[176:179], v[26:29]
	v_mfma_f32_16x16x32_bf16 v[22:25], v[160:163], v[184:187], v[22:25]
	v_mfma_f32_16x16x32_bf16 v[18:21], v[168:171], v[184:187], v[18:21]
	v_mfma_f32_16x16x32_bf16 v[14:17], v[160:163], v[192:195], v[14:17]
	v_mfma_f32_16x16x32_bf16 v[10:13], v[168:171], v[192:195], v[10:13]
	v_mfma_f32_16x16x32_bf16 v[6:9], v[160:163], v[200:203], v[6:9]
	v_mfma_f32_16x16x32_bf16 v[2:5], v[168:171], v[200:203], v[2:5]
	v_mfma_f32_16x16x32_bf16 v[30:33], v[164:167], v[180:183], v[30:33]
	v_mfma_f32_16x16x32_bf16 v[26:29], v[172:175], v[180:183], v[26:29]
	v_mfma_f32_16x16x32_bf16 v[22:25], v[164:167], v[188:191], v[22:25]
	v_mfma_f32_16x16x32_bf16 v[18:21], v[172:175], v[188:191], v[18:21]
	v_mfma_f32_16x16x32_bf16 v[14:17], v[164:167], v[196:199], v[14:17]
	v_mfma_f32_16x16x32_bf16 v[10:13], v[172:175], v[196:199], v[10:13]
	v_mfma_f32_16x16x32_bf16 v[6:9], v[164:167], v[208:211], v[6:9]
	v_mfma_f32_16x16x32_bf16 v[2:5], v[172:175], v[208:211], v[2:5]
	s_barrier
; #define PG8_STAGE(bufoff, gbase, voff) do { _Pragma("unroll") for (int _i = 0; _i < 2; ++_i) \
;         __builtin_amdgcn_global_load_lds((const unsigned*)((const char*)(gbase) + (voff)[_i]), (LAS unsigned*)(lds + (bufoff) + ldsw + _i * 8192), 16, 0, 0); } while (0)
; #define PG8_LDA(dst, b, h) do { _Pragma("unroll") for (int m = 0; m < NM; ++m) _Pragma("unroll") for (int k = 0; k < 2; ++k) dst[m][k] = *(const LAS bf16x8*)(lds + PG8_SA(b, h) + aoff + m * 2048 + k * 1024); } while (0)
; #define PG8_LDB(dst, b, h) do { _Pragma("unroll") for (int n = 0; n < 2; ++n) _Pragma("unroll") for (int k = 0; k < 2; ++k) dst[n][k] = *(const LAS bf16x8*)(lds + PG8_SB(b, h) + boff + n * 2048 + k * 1024); } while (0)
; #define PG8_MMA(ai, bj, At, Bt) do { __builtin_amdgcn_s_setprio(1); _Pragma("unroll") for (int m = 0; m < NM; ++m) _Pragma("unroll") for (int n = 0; n < 2; ++n) _Pragma("unroll") for (int k = 0; k < 2; ++k) \
;         acc[ai][bj][m][n] = __builtin_amdgcn_mfma_f32_16x16x32_bf16(Bt[n][k], At[m][k], acc[ai][bj][m][n], 0, 0, 0); __builtin_amdgcn_s_setprio(0); } while (0)
; #define PG8_WAIT_V(n) asm volatile("s_waitcnt vmcnt(" #n ")" ::: "memory")
; #define PG8_WAIT_L(n) asm volatile("s_waitcnt lgkmcnt(" #n ")" ::: "memory")
; #define PG8_BAR __builtin_amdgcn_s_barrier()
; #define PG8_SCHED __builtin_amdgcn_sched_barrier(0)
;     ...
;             PG8_LDB(B0, 1, 0); PG8_LDB(B1, 1, 1); PG8_SCHED; PG8_LDA(At, 1, 0); PG8_STAGE(PG8_SA(0, 1), a2 + hstepA, voffA);
;             PG8_WAIT_V(8); PG8_WAIT_L(0); PG8_BAR; PG8_MMA(0, 0, At, B0); PG8_MMA(0, 1, At, B1); PG8_BAR; PG8_SCHED;
;             PG8_LDA(At, 1, 1); PG8_STAGE(PG8_SB(1, 0), b3, voffB); PG8_STAGE(PG8_SB(1, 1), b3 + hstepB, voffB); PG8_STAGE(PG8_SA(1, 0), a3, voffA);
;             PG8_WAIT_V(8); PG8_WAIT_L(0); PG8_BAR; PG8_MMA(1, 0, At, B0); PG8_MMA(1, 1, At, B1); PG8_BAR; PG8_SCHED;
	s_setprio 0
	v_add_u32_e32 v156, s50, v142
	v_add_u32_e32 v172, s57, v142
	ds_read_b128 v[144:147], v156
	ds_read_b128 v[148:151], v156 offset:1024
	ds_read_b128 v[152:155], v156 offset:2048
	ds_read_b128 v[156:159], v156 offset:3072
	ds_read_b128 v[160:163], v172
	ds_read_b128 v[164:167], v172 offset:1024
	ds_read_b128 v[168:171], v172 offset:2048
	ds_read_b128 v[172:175], v172 offset:3072
	s_add_u32 s20, s24, 0x24000
	s_addc_u32 s21, s25, 0
	s_mov_b32 m0, s48
	ds_read_b128 v[176:179], v143 offset:32768
	ds_read_b128 v[180:183], v143 offset:33792
	ds_read_b128 v[184:187], v143 offset:34816
	ds_read_b128 v[188:191], v143 offset:35840
	ds_read_b128 v[192:195], v143 offset:36864
	ds_read_b128 v[196:199], v143 offset:37888
	ds_read_b128 v[200:203], v143 offset:38912
	ds_read_b128 v[208:211], v143 offset:39936
	global_load_lds_dwordx4 v130, s[20:21]
	s_mov_b32 m0, s49
	s_nop 0
	global_load_lds_dwordx4 v132, s[20:21]
	s_waitcnt vmcnt(8)
	s_waitcnt lgkmcnt(0)
	s_setprio 1
	s_barrier
	v_mfma_f32_16x16x32_bf16 v[126:129], v[144:147], v[176:179], v[126:129]
	v_mfma_f32_16x16x32_bf16 v[122:125], v[152:155], v[176:179], v[122:125]
	v_mfma_f32_16x16x32_bf16 v[118:121], v[144:147], v[184:187], v[118:121]
	v_mfma_f32_16x16x32_bf16 v[114:117], v[152:155], v[184:187], v[114:117]
	v_mfma_f32_16x16x32_bf16 v[110:113], v[144:147], v[192:195], v[110:113]
	v_mfma_f32_16x16x32_bf16 v[106:109], v[152:155], v[192:195], v[106:109]
	v_mfma_f32_16x16x32_bf16 v[102:105], v[144:147], v[200:203], v[102:105]
	v_mfma_f32_16x16x32_bf16 v[98:101], v[152:155], v[200:203], v[98:101]
	v_mfma_f32_16x16x32_bf16 v[126:129], v[148:151], v[180:183], v[126:129]
	v_mfma_f32_16x16x32_bf16 v[122:125], v[156:159], v[180:183], v[122:125]
	v_mfma_f32_16x16x32_bf16 v[118:121], v[148:151], v[188:191], v[118:121]
	v_mfma_f32_16x16x32_bf16 v[114:117], v[156:159], v[188:191], v[114:117]
	v_mfma_f32_16x16x32_bf16 v[110:113], v[148:151], v[196:199], v[110:113]
	v_mfma_f32_16x16x32_bf16 v[106:109], v[156:159], v[196:199], v[106:109]
	v_mfma_f32_16x16x32_bf16 v[102:105], v[148:151], v[208:211], v[102:105]
	v_mfma_f32_16x16x32_bf16 v[98:101], v[156:159], v[208:211], v[98:101]
	s_setprio 0
	s_setprio 1
	v_mfma_f32_16x16x32_bf16 v[62:65], v[160:163], v[176:179], v[62:65]
	v_mfma_f32_16x16x32_bf16 v[58:61], v[168:171], v[176:179], v[58:61]
	v_mfma_f32_16x16x32_bf16 v[54:57], v[160:163], v[184:187], v[54:57]
	v_mfma_f32_16x16x32_bf16 v[50:53], v[168:171], v[184:187], v[50:53]
	v_mfma_f32_16x16x32_bf16 v[46:49], v[160:163], v[192:195], v[46:49]
	v_mfma_f32_16x16x32_bf16 v[42:45], v[168:171], v[192:195], v[42:45]
	v_mfma_f32_16x16x32_bf16 v[38:41], v[160:163], v[200:203], v[38:41]
	v_mfma_f32_16x16x32_bf16 v[34:37], v[168:171], v[200:203], v[34:37]
	v_mfma_f32_16x16x32_bf16 v[62:65], v[164:167], v[180:183], v[62:65]
	v_mfma_f32_16x16x32_bf16 v[58:61], v[172:175], v[180:183], v[58:61]
	v_mfma_f32_16x16x32_bf16 v[54:57], v[164:167], v[188:191], v[54:57]
	v_mfma_f32_16x16x32_bf16 v[50:53], v[172:175], v[188:191], v[50:53]
	v_mfma_f32_16x16x32_bf16 v[46:49], v[164:167], v[196:199], v[46:49]
	v_mfma_f32_16x16x32_bf16 v[42:45], v[172:175], v[196:199], v[42:45]
	v_mfma_f32_16x16x32_bf16 v[38:41], v[164:167], v[208:211], v[38:41]
	v_mfma_f32_16x16x32_bf16 v[34:37], v[172:175], v[208:211], v[34:37]
	s_barrier
	s_setprio 0
	s_mov_b32 m0, s51
	v_lshl_add_u64 v[140:141], v[140:141], 0, s[66:67]
	s_add_u32 s20, s22, 0x20080
	ds_read_b128 v[176:179], v143 offset:49152
	ds_read_b128 v[180:183], v143 offset:50176
	ds_read_b128 v[184:187], v143 offset:51200
	ds_read_b128 v[188:191], v143 offset:52224
	ds_read_b128 v[192:195], v143 offset:53248
	ds_read_b128 v[196:199], v143 offset:54272
	ds_read_b128 v[200:203], v143 offset:55296
	ds_read_b128 v[208:211], v143 offset:56320
	global_load_lds_dwordx4 v[140:141], off
	v_lshl_add_u64 v[140:141], v[204:205], 0, s[66:67]
	s_mov_b32 m0, s52
	s_addc_u32 s21, s23, 0
	global_load_lds_dwordx4 v[140:141], off
	s_mov_b32 m0, s58
	s_nop 0
	global_load_lds_dwordx4 v0, s[20:21]
	s_mov_b32 m0, s59
	s_nop 0
	global_load_lds_dwordx4 v134, s[20:21]
	v_lshl_add_u64 v[140:141], v[206:207], 0, s[66:67]
	s_mov_b32 m0, s54
	s_nop 0
	global_load_lds_dwordx4 v[140:141], off
	v_lshl_add_u64 v[140:141], v[212:213], 0, s[66:67]
	s_mov_b32 m0, s56
	s_nop 0
	global_load_lds_dwordx4 v[140:141], off
	s_waitcnt vmcnt(8)
	s_waitcnt lgkmcnt(0)
	s_setprio 1
	s_barrier
	v_mfma_f32_16x16x32_bf16 v[94:97], v[144:147], v[176:179], v[94:97]
	v_mfma_f32_16x16x32_bf16 v[90:93], v[152:155], v[176:179], v[90:93]
	v_mfma_f32_16x16x32_bf16 v[86:89], v[144:147], v[184:187], v[86:89]
	v_mfma_f32_16x16x32_bf16 v[82:85], v[152:155], v[184:187], v[82:85]
	v_mfma_f32_16x16x32_bf16 v[78:81], v[144:147], v[192:195], v[78:81]
	v_mfma_f32_16x16x32_bf16 v[74:77], v[152:155], v[192:195], v[74:77]
	v_mfma_f32_16x16x32_bf16 v[70:73], v[144:147], v[200:203], v[70:73]
	v_mfma_f32_16x16x32_bf16 v[66:69], v[152:155], v[200:203], v[66:69]
	v_mfma_f32_16x16x32_bf16 v[94:97], v[148:151], v[180:183], v[94:97]
	v_mfma_f32_16x16x32_bf16 v[90:93], v[156:159], v[180:183], v[90:93]
	v_mfma_f32_16x16x32_bf16 v[86:89], v[148:151], v[188:191], v[86:89]
	v_mfma_f32_16x16x32_bf16 v[82:85], v[156:159], v[188:191], v[82:85]
	v_mfma_f32_16x16x32_bf16 v[78:81], v[148:151], v[196:199], v[78:81]
	v_mfma_f32_16x16x32_bf16 v[74:77], v[156:159], v[196:199], v[74:77]
	v_mfma_f32_16x16x32_bf16 v[70:73], v[148:151], v[208:211], v[70:73]
	v_mfma_f32_16x16x32_bf16 v[66:69], v[156:159], v[208:211], v[66:69]
	s_setprio 0
	s_setprio 1
	v_mfma_f32_16x16x32_bf16 v[30:33], v[160:163], v[176:179], v[30:33]
	v_mfma_f32_16x16x32_bf16 v[26:29], v[168:171], v[176:179], v[26:29]
	v_mfma_f32_16x16x32_bf16 v[22:25], v[160:163], v[184:187], v[22:25]
	v_mfma_f32_16x16x32_bf16 v[18:21], v[168:171], v[184:187], v[18:21]
	v_mfma_f32_16x16x32_bf16 v[14:17], v[160:163], v[192:195], v[14:17]
	v_mfma_f32_16x16x32_bf16 v[10:13], v[168:171], v[192:195], v[10:13]
	v_mfma_f32_16x16x32_bf16 v[6:9], v[160:163], v[200:203], v[6:9]
	v_mfma_f32_16x16x32_bf16 v[2:5], v[168:171], v[200:203], v[2:5]
	v_mfma_f32_16x16x32_bf16 v[30:33], v[164:167], v[180:183], v[30:33]
	v_mfma_f32_16x16x32_bf16 v[26:29], v[172:175], v[180:183], v[26:29]
	v_mfma_f32_16x16x32_bf16 v[22:25], v[164:167], v[188:191], v[22:25]
	v_mfma_f32_16x16x32_bf16 v[18:21], v[172:175], v[188:191], v[18:21]
	v_mfma_f32_16x16x32_bf16 v[14:17], v[164:167], v[196:199], v[14:17]
	v_mfma_f32_16x16x32_bf16 v[10:13], v[172:175], v[196:199], v[10:13]
	v_mfma_f32_16x16x32_bf16 v[6:9], v[164:167], v[208:211], v[6:9]
	v_mfma_f32_16x16x32_bf16 v[2:5], v[172:175], v[208:211], v[2:5]
	s_barrier
	s_setprio 0
	s_add_i32 s73, s73, 2
	s_add_u32 s15, s15, 0x100
	s_addc_u32 s60, s60, 0
	s_cmp_gt_u32 s73, 5
	s_mov_b64 s[20:21], s[6:7]
	s_cbranch_scc0 .LBB0_1454
	s_and_b64 vcc, exec, s[12:13]
	s_cbranch_vccz .LBB0_1457
	s_barrier

; #define PG8_STAGE(bufoff, gbase, voff) do { _Pragma("unroll") for (int _i = 0; _i < 2; ++_i) \
;         __builtin_amdgcn_global_load_lds((const unsigned*)((const char*)(gbase) + (voff)[_i]), (LAS unsigned*)(lds + (bufoff) + ldsw + _i * 8192), 16, 0, 0); } while (0)
; #define PG8_LDA(dst, b, h) do { _Pragma("unroll") for (int m = 0; m < NM; ++m) _Pragma("unroll") for (int k = 0; k < 2; ++k) dst[m][k] = *(const LAS bf16x8*)(lds + PG8_SA(b, h) + aoff + m * 2048 + k * 1024); } while (0)
; #define PG8_MMA(ai, bj, At, Bt) do { __builtin_amdgcn_s_setprio(1); _Pragma("unroll") for (int m = 0; m < NM; ++m) _Pragma("unroll") for (int n = 0; n < 2; ++n) _Pragma("unroll") for (int k = 0; k < 2; ++k) \
;         acc[ai][bj][m][n] = __builtin_amdgcn_mfma_f32_16x16x32_bf16(Bt[n][k], At[m][k], acc[ai][bj][m][n], 0, 0, 0); __builtin_amdgcn_s_setprio(0); } while (0)
; #define PG8_WAIT_V(n) asm volatile("s_waitcnt vmcnt(" #n ")" ::: "memory")
; #define PG8_WAIT_L(n) asm volatile("s_waitcnt lgkmcnt(" #n ")" ::: "memory")
; #define PG8_BAR __builtin_amdgcn_s_barrier()
; #define PG8_SCHED __builtin_amdgcn_sched_barrier(0)
;     ...
;             PG8_WAIT_V(8); PG8_WAIT_L(0); PG8_BAR; PG8_MMA(0, 0, At, B0); PG8_MMA(0, 1, At, B1); PG8_BAR; PG8_SCHED;
;             PG8_LDA(At, 0, 1); PG8_STAGE(PG8_SB(0, 0), b2, voffB); PG8_STAGE(PG8_SB(0, 1), b2 + hstepB, voffB); PG8_STAGE(PG8_SA(0, 0), a2, voffA);
.Lnm3o_done0:
	s_waitcnt lgkmcnt(0)
	s_setprio 1
	s_barrier
	v_mfma_f32_16x16x32_bf16 v[110:113], v[90:93], v[130:133], v[110:113]
	v_mfma_f32_16x16x32_bf16 v[106:109], v[98:101], v[130:133], v[106:109]
	v_mfma_f32_16x16x32_bf16 v[78:81], v[90:93], v[138:141], v[78:81]
	v_mfma_f32_16x16x32_bf16 v[74:77], v[98:101], v[138:141], v[74:77]
	v_mfma_f32_16x16x32_bf16 v[62:65], v[90:93], v[156:159], v[62:65]
	v_mfma_f32_16x16x32_bf16 v[58:61], v[98:101], v[156:159], v[58:61]
	v_mfma_f32_16x16x32_bf16 v[110:113], v[94:97], v[134:137], v[110:113]
	v_mfma_f32_16x16x32_bf16 v[106:109], v[102:105], v[134:137], v[106:109]
	v_mfma_f32_16x16x32_bf16 v[78:81], v[94:97], v[152:155], v[78:81]
	v_mfma_f32_16x16x32_bf16 v[74:77], v[102:105], v[152:155], v[74:77]
	v_mfma_f32_16x16x32_bf16 v[62:65], v[94:97], v[160:163], v[62:65]
	v_mfma_f32_16x16x32_bf16 v[58:61], v[102:105], v[160:163], v[58:61]
	s_setprio 0
	s_setprio 1
	v_mfma_f32_16x16x32_bf16 v[86:89], v[114:117], v[130:133], v[86:89]
	v_mfma_f32_16x16x32_bf16 v[82:85], v[122:125], v[130:133], v[82:85]
	v_mfma_f32_16x16x32_bf16 v[70:73], v[114:117], v[138:141], v[70:73]
	v_mfma_f32_16x16x32_bf16 v[66:69], v[122:125], v[138:141], v[66:69]
	v_mfma_f32_16x16x32_bf16 v[54:57], v[114:117], v[156:159], v[54:57]
	v_mfma_f32_16x16x32_bf16 v[50:53], v[122:125], v[156:159], v[50:53]
	v_mfma_f32_16x16x32_bf16 v[86:89], v[118:121], v[134:137], v[86:89]
	v_mfma_f32_16x16x32_bf16 v[82:85], v[126:129], v[134:137], v[82:85]
	v_mfma_f32_16x16x32_bf16 v[70:73], v[118:121], v[152:155], v[70:73]
	v_mfma_f32_16x16x32_bf16 v[66:69], v[126:129], v[152:155], v[66:69]
	v_mfma_f32_16x16x32_bf16 v[54:57], v[118:121], v[160:163], v[54:57]
	v_mfma_f32_16x16x32_bf16 v[50:53], v[126:129], v[160:163], v[50:53]
	s_barrier
	s_setprio 0
	s_mov_b32 m0, s29
	v_lshl_add_u64 v[164:165], s[22:23], 0, v[0:1]
	s_add_u32 s62, s22, 0x80000
	ds_read_b128 v[130:133], v167 offset:16384
	ds_read_b128 v[134:137], v167 offset:17408
	ds_read_b128 v[138:141], v167 offset:18432
	ds_read_b128 v[152:155], v167 offset:19456
	ds_read_b128 v[156:159], v167 offset:20480
	ds_read_b128 v[160:163], v167 offset:21504
	global_load_lds_dwordx4 v0, s[22:23]
	v_lshl_add_u64 v[168:169], s[22:23], 0, v[146:147]
	s_mov_b32 m0, s30
	s_addc_u32 s63, s23, 0
	global_load_lds_dwordx4 v146, s[22:23]
	s_mov_b32 m0, s33
	v_lshl_add_u64 v[172:173], s[24:25], 0, v[144:145]
	global_load_lds_dwordx4 v0, s[62:63]
	s_mov_b32 m0, s34
	s_nop 0
	global_load_lds_dwordx4 v146, s[62:63]
	v_lshl_add_u64 v[170:171], s[24:25], 0, v[142:143]
	s_mov_b32 m0, s35
	s_nop 0
	global_load_lds_dwordx4 v142, s[24:25]
	s_mov_b32 m0, s36
	s_nop 0
	s_and_b64 vcc, exec, s[10:11]
	s_cbranch_vccz .Lnm3o_skip1
	global_load_lds_dwordx4 v144, s[24:25]
	s_waitcnt vmcnt(8)
	s_branch .Lnm3o_done1

; #define PG8_STAGE(bufoff, gbase, voff) do { _Pragma("unroll") for (int _i = 0; _i < 2; ++_i) \
;         __builtin_amdgcn_global_load_lds((const unsigned*)((const char*)(gbase) + (voff)[_i]), (LAS unsigned*)(lds + (bufoff) + ldsw + _i * 8192), 16, 0, 0); } while (0)
; #define PG8_LDA(dst, b, h) do { _Pragma("unroll") for (int m = 0; m < NM; ++m) _Pragma("unroll") for (int k = 0; k < 2; ++k) dst[m][k] = *(const LAS bf16x8*)(lds + PG8_SA(b, h) + aoff + m * 2048 + k * 1024); } while (0)
; #define PG8_LDB(dst, b, h) do { _Pragma("unroll") for (int n = 0; n < 2; ++n) _Pragma("unroll") for (int k = 0; k < 2; ++k) dst[n][k] = *(const LAS bf16x8*)(lds + PG8_SB(b, h) + boff + n * 2048 + k * 1024); } while (0)
; #define PG8_MMA(ai, bj, At, Bt) do { __builtin_amdgcn_s_setprio(1); _Pragma("unroll") for (int m = 0; m < NM; ++m) _Pragma("unroll") for (int n = 0; n < 2; ++n) _Pragma("unroll") for (int k = 0; k < 2; ++k) \
;         acc[ai][bj][m][n] = __builtin_amdgcn_mfma_f32_16x16x32_bf16(Bt[n][k], At[m][k], acc[ai][bj][m][n], 0, 0, 0); __builtin_amdgcn_s_setprio(0); } while (0)
; #define PG8_WAIT_V(n) asm volatile("s_waitcnt vmcnt(" #n ")" ::: "memory")
; #define PG8_WAIT_L(n) asm volatile("s_waitcnt lgkmcnt(" #n ")" ::: "memory")
; #define PG8_BAR __builtin_amdgcn_s_barrier()
; #define PG8_SCHED __builtin_amdgcn_sched_barrier(0)
;     ...
;             PG8_WAIT_V(8); PG8_WAIT_L(0); PG8_BAR; PG8_MMA(1, 0, At, B0); PG8_MMA(1, 1, At, B1); PG8_BAR; PG8_SCHED;
;             PG8_LDB(B0, 1, 0); PG8_LDB(B1, 1, 1); PG8_SCHED; PG8_LDA(At, 1, 0); PG8_STAGE(PG8_SA(0, 1), a2 + hstepA, voffA);
.Lnm3o_done1:
	s_waitcnt lgkmcnt(0)
	s_setprio 1
	s_barrier
	v_mfma_f32_16x16x32_bf16 v[46:49], v[90:93], v[130:133], v[46:49]
	v_mfma_f32_16x16x32_bf16 v[42:45], v[98:101], v[130:133], v[42:45]
	v_mfma_f32_16x16x32_bf16 v[30:33], v[90:93], v[138:141], v[30:33]
	v_mfma_f32_16x16x32_bf16 v[26:29], v[98:101], v[138:141], v[26:29]
	v_mfma_f32_16x16x32_bf16 v[14:17], v[90:93], v[156:159], v[14:17]
	v_mfma_f32_16x16x32_bf16 v[10:13], v[98:101], v[156:159], v[10:13]
	v_mfma_f32_16x16x32_bf16 v[46:49], v[94:97], v[134:137], v[46:49]
	v_mfma_f32_16x16x32_bf16 v[42:45], v[102:105], v[134:137], v[42:45]
	v_mfma_f32_16x16x32_bf16 v[30:33], v[94:97], v[152:155], v[30:33]
	v_mfma_f32_16x16x32_bf16 v[26:29], v[102:105], v[152:155], v[26:29]
	v_mfma_f32_16x16x32_bf16 v[14:17], v[94:97], v[160:163], v[14:17]
	v_mfma_f32_16x16x32_bf16 v[10:13], v[102:105], v[160:163], v[10:13]
	s_setprio 0
	s_setprio 1
	v_mfma_f32_16x16x32_bf16 v[38:41], v[114:117], v[130:133], v[38:41]
	v_mfma_f32_16x16x32_bf16 v[34:37], v[122:125], v[130:133], v[34:37]
	v_mfma_f32_16x16x32_bf16 v[22:25], v[114:117], v[138:141], v[22:25]
	v_mfma_f32_16x16x32_bf16 v[18:21], v[122:125], v[138:141], v[18:21]
	v_mfma_f32_16x16x32_bf16 v[6:9], v[114:117], v[156:159], v[6:9]
	v_mfma_f32_16x16x32_bf16 v[2:5], v[122:125], v[156:159], v[2:5]
	v_mfma_f32_16x16x32_bf16 v[38:41], v[118:121], v[134:137], v[38:41]
	v_mfma_f32_16x16x32_bf16 v[34:37], v[126:129], v[134:137], v[34:37]
	v_mfma_f32_16x16x32_bf16 v[22:25], v[118:121], v[152:155], v[22:25]
	v_mfma_f32_16x16x32_bf16 v[18:21], v[126:129], v[152:155], v[18:21]
	v_mfma_f32_16x16x32_bf16 v[6:9], v[118:121], v[160:163], v[6:9]
	v_mfma_f32_16x16x32_bf16 v[2:5], v[126:129], v[160:163], v[2:5]
	s_barrier
	s_setprio 0
	v_add_u32_e32 v102, s40, v166
	v_add_u32_e32 v126, s45, v166
	ds_read_b128 v[90:93], v102
	ds_read_b128 v[94:97], v102 offset:1024
	ds_read_b128 v[98:101], v102 offset:2048
	ds_read_b128 v[102:105], v102 offset:3072
	ds_read_b128 v[114:117], v126
	ds_read_b128 v[118:121], v126 offset:1024
	ds_read_b128 v[122:125], v126 offset:2048
	ds_read_b128 v[126:129], v126 offset:3072
	s_add_u32 s24, s24, 0x60000
	s_addc_u32 s25, s25, 0
	s_mov_b32 m0, s37
	ds_read_b128 v[130:133], v167 offset:32768
	ds_read_b128 v[134:137], v167 offset:33792
	ds_read_b128 v[138:141], v167 offset:34816
	ds_read_b128 v[152:155], v167 offset:35840
	ds_read_b128 v[156:159], v167 offset:36864
	ds_read_b128 v[160:163], v167 offset:37888
	global_load_lds_dwordx4 v142, s[24:25]
	s_mov_b32 m0, s38
	s_nop 0
	s_and_b64 vcc, exec, s[10:11]
	s_cbranch_vccz .Lnm3o_skip2
	global_load_lds_dwordx4 v144, s[24:25]
	s_waitcnt vmcnt(8)
	s_branch .Lnm3o_done2

; #define PG8_STAGE(bufoff, gbase, voff) do { _Pragma("unroll") for (int _i = 0; _i < 2; ++_i) \
;         __builtin_amdgcn_global_load_lds((const unsigned*)((const char*)(gbase) + (voff)[_i]), (LAS unsigned*)(lds + (bufoff) + ldsw + _i * 8192), 16, 0, 0); } while (0)
; #define PG8_LDA(dst, b, h) do { _Pragma("unroll") for (int m = 0; m < NM; ++m) _Pragma("unroll") for (int k = 0; k < 2; ++k) dst[m][k] = *(const LAS bf16x8*)(lds + PG8_SA(b, h) + aoff + m * 2048 + k * 1024); } while (0)
; #define PG8_MMA(ai, bj, At, Bt) do { __builtin_amdgcn_s_setprio(1); _Pragma("unroll") for (int m = 0; m < NM; ++m) _Pragma("unroll") for (int n = 0; n < 2; ++n) _Pragma("unroll") for (int k = 0; k < 2; ++k) \
;         acc[ai][bj][m][n] = __builtin_amdgcn_mfma_f32_16x16x32_bf16(Bt[n][k], At[m][k], acc[ai][bj][m][n], 0, 0, 0); __builtin_amdgcn_s_setprio(0); } while (0)
; #define PG8_WAIT_V(n) asm volatile("s_waitcnt vmcnt(" #n ")" ::: "memory")
; #define PG8_WAIT_L(n) asm volatile("s_waitcnt lgkmcnt(" #n ")" ::: "memory")
; #define PG8_BAR __builtin_amdgcn_s_barrier()
; #define PG8_SCHED __builtin_amdgcn_sched_barrier(0)
;     ...
;             PG8_WAIT_V(8); PG8_WAIT_L(0); PG8_BAR; PG8_MMA(0, 0, At, B0); PG8_MMA(0, 1, At, B1); PG8_BAR; PG8_SCHED;
;             PG8_LDA(At, 1, 1); PG8_STAGE(PG8_SB(1, 0), b3, voffB); PG8_STAGE(PG8_SB(1, 1), b3 + hstepB, voffB); PG8_STAGE(PG8_SA(1, 0), a3, voffA);
;             PG8_WAIT_V(8); PG8_WAIT_L(0); PG8_BAR; PG8_MMA(1, 0, At, B0); PG8_MMA(1, 1, At, B1); PG8_BAR; PG8_SCHED;
.Lnm3o_done2:
	s_waitcnt lgkmcnt(0)
	s_setprio 1
	s_barrier
	v_mfma_f32_16x16x32_bf16 v[110:113], v[90:93], v[130:133], v[110:113]
	v_mfma_f32_16x16x32_bf16 v[106:109], v[98:101], v[130:133], v[106:109]
	v_mfma_f32_16x16x32_bf16 v[78:81], v[90:93], v[138:141], v[78:81]
	v_mfma_f32_16x16x32_bf16 v[74:77], v[98:101], v[138:141], v[74:77]
	v_mfma_f32_16x16x32_bf16 v[62:65], v[90:93], v[156:159], v[62:65]
	v_mfma_f32_16x16x32_bf16 v[58:61], v[98:101], v[156:159], v[58:61]
	v_mfma_f32_16x16x32_bf16 v[110:113], v[94:97], v[134:137], v[110:113]
	v_mfma_f32_16x16x32_bf16 v[106:109], v[102:105], v[134:137], v[106:109]
	v_mfma_f32_16x16x32_bf16 v[78:81], v[94:97], v[152:155], v[78:81]
	v_mfma_f32_16x16x32_bf16 v[74:77], v[102:105], v[152:155], v[74:77]
	v_mfma_f32_16x16x32_bf16 v[62:65], v[94:97], v[160:163], v[62:65]
	v_mfma_f32_16x16x32_bf16 v[58:61], v[102:105], v[160:163], v[58:61]
	s_setprio 0
	s_setprio 1
	v_mfma_f32_16x16x32_bf16 v[86:89], v[114:117], v[130:133], v[86:89]
	v_mfma_f32_16x16x32_bf16 v[82:85], v[122:125], v[130:133], v[82:85]
	v_mfma_f32_16x16x32_bf16 v[70:73], v[114:117], v[138:141], v[70:73]
	v_mfma_f32_16x16x32_bf16 v[66:69], v[122:125], v[138:141], v[66:69]
	v_mfma_f32_16x16x32_bf16 v[54:57], v[114:117], v[156:159], v[54:57]
	v_mfma_f32_16x16x32_bf16 v[50:53], v[122:125], v[156:159], v[50:53]
	v_mfma_f32_16x16x32_bf16 v[86:89], v[118:121], v[134:137], v[86:89]
	v_mfma_f32_16x16x32_bf16 v[82:85], v[126:129], v[134:137], v[82:85]
	v_mfma_f32_16x16x32_bf16 v[70:73], v[118:121], v[152:155], v[70:73]
	v_mfma_f32_16x16x32_bf16 v[66:69], v[126:129], v[152:155], v[66:69]
	v_mfma_f32_16x16x32_bf16 v[54:57], v[118:121], v[160:163], v[54:57]
	v_mfma_f32_16x16x32_bf16 v[50:53], v[126:129], v[160:163], v[50:53]
	s_barrier
	s_setprio 0
	s_mov_b32 m0, s41
	v_lshl_add_u64 v[164:165], v[164:165], 0, s[66:67]
	s_add_u32 s22, s22, 0x80080
	ds_read_b128 v[130:133], v167 offset:49152
	ds_read_b128 v[134:137], v167 offset:50176
	ds_read_b128 v[138:141], v167 offset:51200
	ds_read_b128 v[152:155], v167 offset:52224
	ds_read_b128 v[156:159], v167 offset:53248
	ds_read_b128 v[160:163], v167 offset:54272
	global_load_lds_dwordx4 v[164:165], off
	v_lshl_add_u64 v[164:165], v[168:169], 0, s[66:67]
	s_mov_b32 m0, s42
	s_addc_u32 s23, s23, 0
	global_load_lds_dwordx4 v[164:165], off
	s_mov_b32 m0, s46
	s_nop 0
	global_load_lds_dwordx4 v0, s[22:23]
	s_mov_b32 m0, s47
	s_nop 0
	global_load_lds_dwordx4 v146, s[22:23]
	v_lshl_add_u64 v[164:165], v[170:171], 0, s[66:67]
	s_mov_b32 m0, s43
	s_nop 0
	global_load_lds_dwordx4 v[164:165], off
	v_lshl_add_u64 v[164:165], v[172:173], 0, s[66:67]
	s_mov_b32 m0, s44
	s_nop 0
	s_and_b64 vcc, exec, s[10:11]
	s_cbranch_vccz .Lnm3o_skip3
	global_load_lds_dwordx4 v[164:165], off
	s_waitcnt vmcnt(8)
	s_branch .Lnm3o_done3
.Lnm3o_skip3:
	s_waitcnt vmcnt(6)
.Lnm3o_done3:
	s_waitcnt lgkmcnt(0)
	s_setprio 1
	s_barrier
	v_mfma_f32_16x16x32_bf16 v[46:49], v[90:93], v[130:133], v[46:49]
	v_mfma_f32_16x16x32_bf16 v[42:45], v[98:101], v[130:133], v[42:45]
	v_mfma_f32_16x16x32_bf16 v[30:33], v[90:93], v[138:141], v[30:33]
	v_mfma_f32_16x16x32_bf16 v[26:29], v[98:101], v[138:141], v[26:29]
	v_mfma_f32_16x16x32_bf16 v[14:17], v[90:93], v[156:159], v[14:17]
	v_mfma_f32_16x16x32_bf16 v[10:13], v[98:101], v[156:159], v[10:13]
	v_mfma_f32_16x16x32_bf16 v[46:49], v[94:97], v[134:137], v[46:49]
	v_mfma_f32_16x16x32_bf16 v[42:45], v[102:105], v[134:137], v[42:45]
	v_mfma_f32_16x16x32_bf16 v[30:33], v[94:97], v[152:155], v[30:33]
	v_mfma_f32_16x16x32_bf16 v[26:29], v[102:105], v[152:155], v[26:29]
	v_mfma_f32_16x16x32_bf16 v[14:17], v[94:97], v[160:163], v[14:17]
	v_mfma_f32_16x16x32_bf16 v[10:13], v[102:105], v[160:163], v[10:13]
	s_setprio 0
	s_setprio 1
	v_mfma_f32_16x16x32_bf16 v[38:41], v[114:117], v[130:133], v[38:41]
	v_mfma_f32_16x16x32_bf16 v[34:37], v[122:125], v[130:133], v[34:37]
	v_mfma_f32_16x16x32_bf16 v[22:25], v[114:117], v[138:141], v[22:25]
	v_mfma_f32_16x16x32_bf16 v[18:21], v[122:125], v[138:141], v[18:21]
	v_mfma_f32_16x16x32_bf16 v[6:9], v[114:117], v[156:159], v[6:9]
	v_mfma_f32_16x16x32_bf16 v[2:5], v[122:125], v[156:159], v[2:5]
	v_mfma_f32_16x16x32_bf16 v[38:41], v[118:121], v[134:137], v[38:41]
	v_mfma_f32_16x16x32_bf16 v[34:37], v[126:129], v[134:137], v[34:37]
	v_mfma_f32_16x16x32_bf16 v[22:25], v[118:121], v[152:155], v[22:25]
	v_mfma_f32_16x16x32_bf16 v[18:21], v[126:129], v[152:155], v[18:21]
	v_mfma_f32_16x16x32_bf16 v[6:9], v[118:121], v[160:163], v[6:9]
	v_mfma_f32_16x16x32_bf16 v[2:5], v[126:129], v[160:163], v[2:5]
	s_barrier
	s_setprio 0
	s_add_i32 s59, s59, 2
	s_add_u32 s8, s8, 0x100
	s_addc_u32 s9, s9, 0
	s_add_u32 s15, s15, 0x100
	s_addc_u32 s58, s58, 0
	s_cmp_gt_u32 s59, 29
	s_cbranch_scc0 .LBB0_1650
	s_and_b64 vcc, exec, s[10:11]
	s_cbranch_vccz .LBB0_1653
	s_barrier

; #define PG8_STAGE(bufoff, gbase, voff) do { _Pragma("unroll") for (int _i = 0; _i < 2; ++_i) \
;         __builtin_amdgcn_global_load_lds((const unsigned*)((const char*)(gbase) + (voff)[_i]), (LAS unsigned*)(lds + (bufoff) + ldsw + _i * 8192), 16, 0, 0); } while (0)
; #define PG8_LDA(dst, b, h) do { _Pragma("unroll") for (int m = 0; m < NM; ++m) _Pragma("unroll") for (int k = 0; k < 2; ++k) dst[m][k] = *(const LAS bf16x8*)(lds + PG8_SA(b, h) + aoff + m * 2048 + k * 1024); } while (0)
; #define PG8_LDB(dst, b, h) do { _Pragma("unroll") for (int n = 0; n < 2; ++n) _Pragma("unroll") for (int k = 0; k < 2; ++k) dst[n][k] = *(const LAS bf16x8*)(lds + PG8_SB(b, h) + boff + n * 2048 + k * 1024); } while (0)
; #define PG8_MMA(ai, bj, At, Bt) do { __builtin_amdgcn_s_setprio(1); _Pragma("unroll") for (int m = 0; m < NM; ++m) _Pragma("unroll") for (int n = 0; n < 2; ++n) _Pragma("unroll") for (int k = 0; k < 2; ++k) \
;         acc[ai][bj][m][n] = __builtin_amdgcn_mfma_f32_16x16x32_bf16(Bt[n][k], At[m][k], acc[ai][bj][m][n], 0, 0, 0); __builtin_amdgcn_s_setprio(0); } while (0)
; #define PG8_WAIT_V(n) asm volatile("s_waitcnt vmcnt(" #n ")" ::: "memory")
; #define PG8_WAIT_L(n) asm volatile("s_waitcnt lgkmcnt(" #n ")" ::: "memory")
; #define PG8_BAR __builtin_amdgcn_s_barrier()
; #define PG8_SCHED __builtin_amdgcn_sched_barrier(0)
;     ...
;             const bool last = (t == nt - 2);
;             const char* a1 = cA + (size_t)(t + 1) * kstep;
;             const char* a2 = last ? nA : cA + (size_t)(t + 2) * kstep; const char* b2 = last ? nB : cB + (size_t)(t + 2) * kstep;
;             const char* a3 = a2 + kstep; const char* b3 = b2 + kstep;
;             if constexpr (SP2) {
;             PG8_LDB(B0, 0, 0); PG8_LDB(B1, 0, 1); PG8_SCHED; PG8_LDA(At, 0, 0); PG8_STAGE(PG8_SA(1, 1), a1 + hstepA, voffA);
;             PG8_WAIT_V(8); PG8_WAIT_L(0); PG8_BAR; PG8_MMA(0, 0, At, B0); PG8_MMA(0, 1, At, B1); PG8_BAR; PG8_SCHED;
;             PG8_LDA(At, 0, 1); PG8_STAGE(PG8_SB(0, 0), b2, voffB); PG8_STAGE(PG8_SB(0, 1), b2 + hstepB, voffB); PG8_STAGE(PG8_SA(0, 0), a2, voffA);
;             PG8_WAIT_V(8); PG8_WAIT_L(0); PG8_BAR; PG8_MMA(1, 0, At, B0); PG8_MMA(1, 1, At, B1); PG8_BAR; PG8_SCHED;
.LBB0_1783:
	v_add_u32_e32 v0, s64, v208
	ds_read_b128 v[130:133], v0
	ds_read_b128 v[134:137], v0 offset:1024
	ds_read_b128 v[138:141], v0 offset:2048
	ds_read_b128 v[142:145], v0 offset:3072
	v_add_u32_e32 v0, s70, v208
	ds_read_b128 v[146:149], v0
	ds_read_b128 v[150:153], v0 offset:1024
	ds_read_b128 v[154:157], v0 offset:2048
	ds_read_b128 v[158:161], v0 offset:3072
	s_add_u32 s14, s12, 0xfff80080
	s_addc_u32 s15, s13, -1
	s_cmp_eq_u32 vcc_lo, 28
	s_cselect_b32 s47, s2, s15
	s_cselect_b32 s46, s3, s14
	s_cselect_b32 s15, s9, s41
	s_cselect_b32 s14, s11, s37
	s_add_i32 m0, s73, 0xc000
	ds_read_b128 v[162:165], v209
	ds_read_b128 v[166:169], v209 offset:1024
	ds_read_b128 v[170:173], v209 offset:2048
	ds_read_b128 v[174:177], v209 offset:3072
	ds_read_b128 v[190:193], v209 offset:4096
	ds_read_b128 v[194:197], v209 offset:5120
	ds_read_b128 v[198:201], v209 offset:6144
	ds_read_b128 v[202:205], v209 offset:7168
	global_load_lds_dwordx4 v186, s[12:13]
	s_add_i32 m0, s73, 0xe000
	s_nop 0
	global_load_lds_dwordx4 v188, s[12:13]
	s_waitcnt vmcnt(8)
	s_waitcnt lgkmcnt(0)
	s_setprio 1
	s_barrier
	v_mfma_f32_16x16x32_bf16 v[126:129], v[130:133], v[162:165], v[126:129]
	v_mfma_f32_16x16x32_bf16 v[94:97], v[138:141], v[162:165], v[94:97]
	v_mfma_f32_16x16x32_bf16 v[110:113], v[130:133], v[170:173], v[110:113]
	v_mfma_f32_16x16x32_bf16 v[70:73], v[138:141], v[170:173], v[70:73]
	v_mfma_f32_16x16x32_bf16 v[106:109], v[130:133], v[190:193], v[106:109]
	v_mfma_f32_16x16x32_bf16 v[66:69], v[138:141], v[190:193], v[66:69]
	v_mfma_f32_16x16x32_bf16 v[118:121], v[130:133], v[198:201], v[118:121]
	v_mfma_f32_16x16x32_bf16 v[86:89], v[138:141], v[198:201], v[86:89]
	v_mfma_f32_16x16x32_bf16 v[126:129], v[134:137], v[166:169], v[126:129]
	v_mfma_f32_16x16x32_bf16 v[94:97], v[142:145], v[166:169], v[94:97]
	v_mfma_f32_16x16x32_bf16 v[110:113], v[134:137], v[174:177], v[110:113]
	v_mfma_f32_16x16x32_bf16 v[70:73], v[142:145], v[174:177], v[70:73]
	v_mfma_f32_16x16x32_bf16 v[106:109], v[134:137], v[194:197], v[106:109]
	v_mfma_f32_16x16x32_bf16 v[66:69], v[142:145], v[194:197], v[66:69]
	v_mfma_f32_16x16x32_bf16 v[118:121], v[134:137], v[202:205], v[118:121]
	v_mfma_f32_16x16x32_bf16 v[86:89], v[142:145], v[202:205], v[86:89]
	s_setprio 0
	s_setprio 1
	v_mfma_f32_16x16x32_bf16 v[122:125], v[146:149], v[162:165], v[122:125]
	v_mfma_f32_16x16x32_bf16 v[90:93], v[154:157], v[162:165], v[90:93]
	v_mfma_f32_16x16x32_bf16 v[102:105], v[146:149], v[170:173], v[102:105]
	v_mfma_f32_16x16x32_bf16 v[62:65], v[154:157], v[170:173], v[62:65]
	v_mfma_f32_16x16x32_bf16 v[98:101], v[146:149], v[190:193], v[98:101]
	v_mfma_f32_16x16x32_bf16 v[58:61], v[154:157], v[190:193], v[58:61]
	v_mfma_f32_16x16x32_bf16 v[114:117], v[146:149], v[198:201], v[114:117]
	v_mfma_f32_16x16x32_bf16 v[82:85], v[154:157], v[198:201], v[82:85]
	v_mfma_f32_16x16x32_bf16 v[122:125], v[150:153], v[166:169], v[122:125]
	v_mfma_f32_16x16x32_bf16 v[90:93], v[158:161], v[166:169], v[90:93]
	v_mfma_f32_16x16x32_bf16 v[102:105], v[150:153], v[174:177], v[102:105]
	v_mfma_f32_16x16x32_bf16 v[62:65], v[158:161], v[174:177], v[62:65]
	v_mfma_f32_16x16x32_bf16 v[98:101], v[150:153], v[194:197], v[98:101]
	v_mfma_f32_16x16x32_bf16 v[58:61], v[158:161], v[194:197], v[58:61]
	v_mfma_f32_16x16x32_bf16 v[114:117], v[150:153], v[202:205], v[114:117]
	v_mfma_f32_16x16x32_bf16 v[82:85], v[158:161], v[202:205], v[82:85]
	s_barrier
	s_setprio 0
	s_mov_b32 m0, s68
	s_add_u32 s22, s14, 0x80000
	ds_read_b128 v[162:165], v209 offset:16384
	ds_read_b128 v[166:169], v209 offset:17408
	ds_read_b128 v[170:173], v209 offset:18432
	ds_read_b128 v[174:177], v209 offset:19456
	ds_read_b128 v[190:193], v209 offset:20480
	ds_read_b128 v[194:197], v209 offset:21504
	ds_read_b128 v[198:201], v209 offset:22528
	ds_read_b128 v[202:205], v209 offset:23552
	global_load_lds_dwordx4 v180, s[14:15]
	s_mov_b32 m0, s69
	s_addc_u32 s23, s15, 0
	global_load_lds_dwordx4 v184, s[14:15]
	s_mov_b32 m0, s71
	s_nop 0
	global_load_lds_dwordx4 v180, s[22:23]
	s_mov_b32 m0, s72
	s_nop 0
	global_load_lds_dwordx4 v184, s[22:23]
	s_mov_b32 m0, s73
	s_nop 0
	global_load_lds_dwordx4 v178, s[46:47]
	s_mov_b32 m0, s74
	s_nop 0
	global_load_lds_dwordx4 v182, s[46:47]
	s_waitcnt vmcnt(8)
	s_waitcnt lgkmcnt(0)
	s_setprio 1
	s_barrier
	v_mfma_f32_16x16x32_bf16 v[46:49], v[130:133], v[162:165], v[46:49]
	v_mfma_f32_16x16x32_bf16 v[22:25], v[138:141], v[162:165], v[22:25]
	v_mfma_f32_16x16x32_bf16 v[42:45], v[130:133], v[170:173], v[42:45]
	v_mfma_f32_16x16x32_bf16 v[18:21], v[138:141], v[170:173], v[18:21]
	v_mfma_f32_16x16x32_bf16 v[38:41], v[130:133], v[190:193], v[38:41]
	v_mfma_f32_16x16x32_bf16 v[14:17], v[138:141], v[190:193], v[14:17]
	v_mfma_f32_16x16x32_bf16 v[78:81], v[130:133], v[198:201], v[78:81]
	v_mfma_f32_16x16x32_bf16 v[54:57], v[138:141], v[198:201], v[54:57]
	v_mfma_f32_16x16x32_bf16 v[46:49], v[134:137], v[166:169], v[46:49]
	v_mfma_f32_16x16x32_bf16 v[22:25], v[142:145], v[166:169], v[22:25]
	v_mfma_f32_16x16x32_bf16 v[42:45], v[134:137], v[174:177], v[42:45]
	v_mfma_f32_16x16x32_bf16 v[18:21], v[142:145], v[174:177], v[18:21]
	v_mfma_f32_16x16x32_bf16 v[38:41], v[134:137], v[194:197], v[38:41]
	v_mfma_f32_16x16x32_bf16 v[14:17], v[142:145], v[194:197], v[14:17]
	v_mfma_f32_16x16x32_bf16 v[78:81], v[134:137], v[202:205], v[78:81]
	v_mfma_f32_16x16x32_bf16 v[54:57], v[142:145], v[202:205], v[54:57]
	s_setprio 0
	s_setprio 1
	v_mfma_f32_16x16x32_bf16 v[34:37], v[146:149], v[162:165], v[34:37]
	v_mfma_f32_16x16x32_bf16 v[10:13], v[154:157], v[162:165], v[10:13]
	v_mfma_f32_16x16x32_bf16 v[30:33], v[146:149], v[170:173], v[30:33]
	v_mfma_f32_16x16x32_bf16 v[6:9], v[154:157], v[170:173], v[6:9]
	v_mfma_f32_16x16x32_bf16 v[26:29], v[146:149], v[190:193], v[26:29]
	v_mfma_f32_16x16x32_bf16 v[2:5], v[154:157], v[190:193], v[2:5]
	v_mfma_f32_16x16x32_bf16 v[74:77], v[146:149], v[198:201], v[74:77]
	v_mfma_f32_16x16x32_bf16 v[50:53], v[154:157], v[198:201], v[50:53]
	v_mfma_f32_16x16x32_bf16 v[34:37], v[150:153], v[166:169], v[34:37]
	v_mfma_f32_16x16x32_bf16 v[10:13], v[158:161], v[166:169], v[10:13]
	v_mfma_f32_16x16x32_bf16 v[30:33], v[150:153], v[174:177], v[30:33]
	v_mfma_f32_16x16x32_bf16 v[6:9], v[158:161], v[174:177], v[6:9]
	v_mfma_f32_16x16x32_bf16 v[26:29], v[150:153], v[194:197], v[26:29]
	v_mfma_f32_16x16x32_bf16 v[2:5], v[158:161], v[194:197], v[2:5]
	v_mfma_f32_16x16x32_bf16 v[74:77], v[150:153], v[202:205], v[74:77]
	v_mfma_f32_16x16x32_bf16 v[50:53], v[158:161], v[202:205], v[50:53]
	s_barrier
; #define PG8_STAGE(bufoff, gbase, voff) do { _Pragma("unroll") for (int _i = 0; _i < 2; ++_i) \
;         __builtin_amdgcn_global_load_lds((const unsigned*)((const char*)(gbase) + (voff)[_i]), (LAS unsigned*)(lds + (bufoff) + ldsw + _i * 8192), 16, 0, 0); } while (0)
; #define PG8_LDA(dst, b, h) do { _Pragma("unroll") for (int m = 0; m < NM; ++m) _Pragma("unroll") for (int k = 0; k < 2; ++k) dst[m][k] = *(const LAS bf16x8*)(lds + PG8_SA(b, h) + aoff + m * 2048 + k * 1024); } while (0)
; #define PG8_LDB(dst, b, h) do { _Pragma("unroll") for (int n = 0; n < 2; ++n) _Pragma("unroll") for (int k = 0; k < 2; ++k) dst[n][k] = *(const LAS bf16x8*)(lds + PG8_SB(b, h) + boff + n * 2048 + k * 1024); } while (0)
; #define PG8_MMA(ai, bj, At, Bt) do { __builtin_amdgcn_s_setprio(1); _Pragma("unroll") for (int m = 0; m < NM; ++m) _Pragma("unroll") for (int n = 0; n < 2; ++n) _Pragma("unroll") for (int k = 0; k < 2; ++k) \
;         acc[ai][bj][m][n] = __builtin_amdgcn_mfma_f32_16x16x32_bf16(Bt[n][k], At[m][k], acc[ai][bj][m][n], 0, 0, 0); __builtin_amdgcn_s_setprio(0); } while (0)
; #define PG8_WAIT_V(n) asm volatile("s_waitcnt vmcnt(" #n ")" ::: "memory")
; #define PG8_WAIT_L(n) asm volatile("s_waitcnt lgkmcnt(" #n ")" ::: "memory")
; #define PG8_BAR __builtin_amdgcn_s_barrier()
; #define PG8_SCHED __builtin_amdgcn_sched_barrier(0)
;     ...
;             PG8_LDB(B0, 1, 0); PG8_LDB(B1, 1, 1); PG8_SCHED; PG8_LDA(At, 1, 0); PG8_STAGE(PG8_SA(0, 1), a2 + hstepA, voffA);
;             PG8_WAIT_V(8); PG8_WAIT_L(0); PG8_BAR; PG8_MMA(0, 0, At, B0); PG8_MMA(0, 1, At, B1); PG8_BAR; PG8_SCHED;
;             PG8_LDA(At, 1, 1); PG8_STAGE(PG8_SB(1, 0), b3, voffB); PG8_STAGE(PG8_SB(1, 1), b3 + hstepB, voffB); PG8_STAGE(PG8_SA(1, 0), a3, voffA);
;             PG8_WAIT_V(8); PG8_WAIT_L(0); PG8_BAR; PG8_MMA(1, 0, At, B0); PG8_MMA(1, 1, At, B1); PG8_BAR; PG8_SCHED;
	s_setprio 0
	v_add_u32_e32 v0, s94, v208
	ds_read_b128 v[130:133], v0
	ds_read_b128 v[134:137], v0 offset:1024
	ds_read_b128 v[138:141], v0 offset:2048
	ds_read_b128 v[142:145], v0 offset:3072
	v_add_u32_e32 v0, s62, v208
	ds_read_b128 v[146:149], v0
	ds_read_b128 v[150:153], v0 offset:1024
	ds_read_b128 v[154:157], v0 offset:2048
	ds_read_b128 v[158:161], v0 offset:3072
	s_add_u32 s22, s46, 0x80000
	s_addc_u32 s23, s47, 0
	s_mov_b32 m0, s75
	ds_read_b128 v[162:165], v209 offset:32768
	ds_read_b128 v[166:169], v209 offset:33792
	ds_read_b128 v[170:173], v209 offset:34816
	ds_read_b128 v[174:177], v209 offset:35840
	ds_read_b128 v[190:193], v209 offset:36864
	ds_read_b128 v[194:197], v209 offset:37888
	ds_read_b128 v[198:201], v209 offset:38912
	ds_read_b128 v[202:205], v209 offset:39936
	global_load_lds_dwordx4 v178, s[22:23]
	s_mov_b32 m0, s80
	s_nop 0
	global_load_lds_dwordx4 v182, s[22:23]
	s_waitcnt vmcnt(8)
	s_waitcnt lgkmcnt(0)
	s_setprio 1
	s_barrier
	v_mfma_f32_16x16x32_bf16 v[126:129], v[130:133], v[162:165], v[126:129]
	v_mfma_f32_16x16x32_bf16 v[94:97], v[138:141], v[162:165], v[94:97]
	v_mfma_f32_16x16x32_bf16 v[110:113], v[130:133], v[170:173], v[110:113]
	v_mfma_f32_16x16x32_bf16 v[70:73], v[138:141], v[170:173], v[70:73]
	v_mfma_f32_16x16x32_bf16 v[106:109], v[130:133], v[190:193], v[106:109]
	v_mfma_f32_16x16x32_bf16 v[66:69], v[138:141], v[190:193], v[66:69]
	v_mfma_f32_16x16x32_bf16 v[118:121], v[130:133], v[198:201], v[118:121]
	v_mfma_f32_16x16x32_bf16 v[86:89], v[138:141], v[198:201], v[86:89]
	v_mfma_f32_16x16x32_bf16 v[126:129], v[134:137], v[166:169], v[126:129]
	v_mfma_f32_16x16x32_bf16 v[94:97], v[142:145], v[166:169], v[94:97]
	v_mfma_f32_16x16x32_bf16 v[110:113], v[134:137], v[174:177], v[110:113]
	v_mfma_f32_16x16x32_bf16 v[70:73], v[142:145], v[174:177], v[70:73]
	v_mfma_f32_16x16x32_bf16 v[106:109], v[134:137], v[194:197], v[106:109]
	v_mfma_f32_16x16x32_bf16 v[66:69], v[142:145], v[194:197], v[66:69]
	v_mfma_f32_16x16x32_bf16 v[118:121], v[134:137], v[202:205], v[118:121]
	v_mfma_f32_16x16x32_bf16 v[86:89], v[142:145], v[202:205], v[86:89]
	s_setprio 0
	s_setprio 1
	v_mfma_f32_16x16x32_bf16 v[122:125], v[146:149], v[162:165], v[122:125]
	v_mfma_f32_16x16x32_bf16 v[90:93], v[154:157], v[162:165], v[90:93]
	v_mfma_f32_16x16x32_bf16 v[102:105], v[146:149], v[170:173], v[102:105]
	v_mfma_f32_16x16x32_bf16 v[62:65], v[154:157], v[170:173], v[62:65]
	v_mfma_f32_16x16x32_bf16 v[98:101], v[146:149], v[190:193], v[98:101]
	v_mfma_f32_16x16x32_bf16 v[58:61], v[154:157], v[190:193], v[58:61]
	v_mfma_f32_16x16x32_bf16 v[114:117], v[146:149], v[198:201], v[114:117]
	v_mfma_f32_16x16x32_bf16 v[82:85], v[154:157], v[198:201], v[82:85]
	v_mfma_f32_16x16x32_bf16 v[122:125], v[150:153], v[166:169], v[122:125]
	v_mfma_f32_16x16x32_bf16 v[90:93], v[158:161], v[166:169], v[90:93]
	v_mfma_f32_16x16x32_bf16 v[102:105], v[150:153], v[174:177], v[102:105]
	v_mfma_f32_16x16x32_bf16 v[62:65], v[158:161], v[174:177], v[62:65]
	v_mfma_f32_16x16x32_bf16 v[98:101], v[150:153], v[194:197], v[98:101]
	v_mfma_f32_16x16x32_bf16 v[58:61], v[158:161], v[194:197], v[58:61]
	v_mfma_f32_16x16x32_bf16 v[114:117], v[150:153], v[202:205], v[114:117]
	v_mfma_f32_16x16x32_bf16 v[82:85], v[158:161], v[202:205], v[82:85]
	s_barrier
	s_setprio 0
	s_mov_b32 m0, s51
	s_add_u32 s100, s14, s66
	s_addc_u32 s101, s15, s67
	s_add_u32 s14, s14, 0x80080
	s_addc_u32 s15, s15, 0
	ds_read_b128 v[162:165], v209 offset:49152
	ds_read_b128 v[166:169], v209 offset:50176
	ds_read_b128 v[170:173], v209 offset:51200
	ds_read_b128 v[174:177], v209 offset:52224
	ds_read_b128 v[190:193], v209 offset:53248
	ds_read_b128 v[194:197], v209 offset:54272
	ds_read_b128 v[198:201], v209 offset:55296
	ds_read_b128 v[202:205], v209 offset:56320
	global_load_lds_dwordx4 v180, s[100:101]
	s_mov_b32 m0, s95
	s_nop 0
	global_load_lds_dwordx4 v184, s[100:101]
	s_add_u32 s100, s46, s66
	s_addc_u32 s101, s47, s67
	s_mov_b32 m0, s50
	s_nop 0
	global_load_lds_dwordx4 v180, s[14:15]
	s_mov_b32 m0, s49
	s_nop 0
	global_load_lds_dwordx4 v184, s[14:15]
	s_mov_b32 m0, s58
	s_nop 0
	global_load_lds_dwordx4 v178, s[100:101]
	s_mov_b32 m0, s59
	s_nop 0
	global_load_lds_dwordx4 v182, s[100:101]
	s_waitcnt vmcnt(8)
	s_waitcnt lgkmcnt(0)
	s_setprio 1
	s_barrier
	v_mfma_f32_16x16x32_bf16 v[46:49], v[130:133], v[162:165], v[46:49]
	v_mfma_f32_16x16x32_bf16 v[22:25], v[138:141], v[162:165], v[22:25]
	v_mfma_f32_16x16x32_bf16 v[42:45], v[130:133], v[170:173], v[42:45]
	v_mfma_f32_16x16x32_bf16 v[18:21], v[138:141], v[170:173], v[18:21]
	v_mfma_f32_16x16x32_bf16 v[38:41], v[130:133], v[190:193], v[38:41]
	v_mfma_f32_16x16x32_bf16 v[14:17], v[138:141], v[190:193], v[14:17]
	v_mfma_f32_16x16x32_bf16 v[78:81], v[130:133], v[198:201], v[78:81]
	v_mfma_f32_16x16x32_bf16 v[54:57], v[138:141], v[198:201], v[54:57]
	v_mfma_f32_16x16x32_bf16 v[46:49], v[134:137], v[166:169], v[46:49]
	v_mfma_f32_16x16x32_bf16 v[22:25], v[142:145], v[166:169], v[22:25]
	v_mfma_f32_16x16x32_bf16 v[42:45], v[134:137], v[174:177], v[42:45]
	v_mfma_f32_16x16x32_bf16 v[18:21], v[142:145], v[174:177], v[18:21]
	v_mfma_f32_16x16x32_bf16 v[38:41], v[134:137], v[194:197], v[38:41]
	v_mfma_f32_16x16x32_bf16 v[14:17], v[142:145], v[194:197], v[14:17]
	v_mfma_f32_16x16x32_bf16 v[78:81], v[134:137], v[202:205], v[78:81]
	v_mfma_f32_16x16x32_bf16 v[54:57], v[142:145], v[202:205], v[54:57]
	s_setprio 0
	s_setprio 1
	v_mfma_f32_16x16x32_bf16 v[34:37], v[146:149], v[162:165], v[34:37]
	v_mfma_f32_16x16x32_bf16 v[10:13], v[154:157], v[162:165], v[10:13]
	v_mfma_f32_16x16x32_bf16 v[30:33], v[146:149], v[170:173], v[30:33]
	v_mfma_f32_16x16x32_bf16 v[6:9], v[154:157], v[170:173], v[6:9]
	v_mfma_f32_16x16x32_bf16 v[26:29], v[146:149], v[190:193], v[26:29]
	v_mfma_f32_16x16x32_bf16 v[2:5], v[154:157], v[190:193], v[2:5]
	v_mfma_f32_16x16x32_bf16 v[74:77], v[146:149], v[198:201], v[74:77]
	v_mfma_f32_16x16x32_bf16 v[50:53], v[154:157], v[198:201], v[50:53]
	v_mfma_f32_16x16x32_bf16 v[34:37], v[150:153], v[166:169], v[34:37]
	v_mfma_f32_16x16x32_bf16 v[10:13], v[158:161], v[166:169], v[10:13]
	v_mfma_f32_16x16x32_bf16 v[30:33], v[150:153], v[174:177], v[30:33]
	v_mfma_f32_16x16x32_bf16 v[6:9], v[158:161], v[174:177], v[6:9]
	v_mfma_f32_16x16x32_bf16 v[26:29], v[150:153], v[194:197], v[26:29]
	v_mfma_f32_16x16x32_bf16 v[2:5], v[158:161], v[194:197], v[2:5]
	v_mfma_f32_16x16x32_bf16 v[74:77], v[150:153], v[202:205], v[74:77]
	v_mfma_f32_16x16x32_bf16 v[50:53], v[158:161], v[202:205], v[50:53]
	s_barrier
	s_setprio 0
	s_add_i32 vcc_lo, vcc_lo, 2
	s_add_u32 s12, s12, 0x100
	s_addc_u32 s13, s13, 0
	s_add_u32 s37, s37, 0x100
	s_addc_u32 s41, s41, 0
	s_cmp_gt_u32 vcc_lo, 29
	s_cbranch_scc0 .LBB0_1783
	s_and_b64 vcc, exec, s[24:25]
	s_cbranch_vccz .LBB0_1786
	s_barrier

; #define PG8_STAGE(bufoff, gbase, voff) do { _Pragma("unroll") for (int _i = 0; _i < 2; ++_i) \
;         __builtin_amdgcn_global_load_lds((const unsigned*)((const char*)(gbase) + (voff)[_i]), (LAS unsigned*)(lds + (bufoff) + ldsw + _i * 8192), 16, 0, 0); } while (0)
; #define PG8_LDA(dst, b, h) do { _Pragma("unroll") for (int m = 0; m < NM; ++m) _Pragma("unroll") for (int k = 0; k < 2; ++k) dst[m][k] = *(const LAS bf16x8*)(lds + PG8_SA(b, h) + aoff + m * 2048 + k * 1024); } while (0)
; #define PG8_MMA(ai, bj, At, Bt) do { __builtin_amdgcn_s_setprio(1); _Pragma("unroll") for (int m = 0; m < NM; ++m) _Pragma("unroll") for (int n = 0; n < 2; ++n) _Pragma("unroll") for (int k = 0; k < 2; ++k) \
;         acc[ai][bj][m][n] = __builtin_amdgcn_mfma_f32_16x16x32_bf16(Bt[n][k], At[m][k], acc[ai][bj][m][n], 0, 0, 0); __builtin_amdgcn_s_setprio(0); } while (0)
; #define PG8_WAIT_V(n) asm volatile("s_waitcnt vmcnt(" #n ")" ::: "memory")
; #define PG8_WAIT_L(n) asm volatile("s_waitcnt lgkmcnt(" #n ")" ::: "memory")
; #define PG8_BAR __builtin_amdgcn_s_barrier()
; #define PG8_SCHED __builtin_amdgcn_sched_barrier(0)
;     ...
;             PG8_WAIT_V(8); PG8_WAIT_L(0); PG8_BAR; PG8_MMA(0, 0, At, B0); PG8_MMA(0, 1, At, B1); PG8_BAR; PG8_SCHED;
;             PG8_LDA(At, 0, 1); PG8_STAGE(PG8_SB(0, 0), b2, voffB); PG8_STAGE(PG8_SB(0, 1), b2 + hstepB, voffB); PG8_STAGE(PG8_SA(0, 0), a2, voffA);
.Lnm3d_done0:
	s_waitcnt lgkmcnt(0)
	s_setprio 1
	s_barrier
	v_mfma_f32_16x16x32_bf16 v[110:113], v[90:93], v[130:133], v[110:113]
	v_mfma_f32_16x16x32_bf16 v[106:109], v[98:101], v[130:133], v[106:109]
	v_mfma_f32_16x16x32_bf16 v[78:81], v[90:93], v[138:141], v[78:81]
	v_mfma_f32_16x16x32_bf16 v[74:77], v[98:101], v[138:141], v[74:77]
	v_mfma_f32_16x16x32_bf16 v[62:65], v[90:93], v[156:159], v[62:65]
	v_mfma_f32_16x16x32_bf16 v[58:61], v[98:101], v[156:159], v[58:61]
	v_mfma_f32_16x16x32_bf16 v[110:113], v[94:97], v[134:137], v[110:113]
	v_mfma_f32_16x16x32_bf16 v[106:109], v[102:105], v[134:137], v[106:109]
	v_mfma_f32_16x16x32_bf16 v[78:81], v[94:97], v[152:155], v[78:81]
	v_mfma_f32_16x16x32_bf16 v[74:77], v[102:105], v[152:155], v[74:77]
	v_mfma_f32_16x16x32_bf16 v[62:65], v[94:97], v[160:163], v[62:65]
	v_mfma_f32_16x16x32_bf16 v[58:61], v[102:105], v[160:163], v[58:61]
	s_setprio 0
	s_setprio 1
	v_mfma_f32_16x16x32_bf16 v[86:89], v[114:117], v[130:133], v[86:89]
	v_mfma_f32_16x16x32_bf16 v[82:85], v[122:125], v[130:133], v[82:85]
	v_mfma_f32_16x16x32_bf16 v[70:73], v[114:117], v[138:141], v[70:73]
	v_mfma_f32_16x16x32_bf16 v[66:69], v[122:125], v[138:141], v[66:69]
	v_mfma_f32_16x16x32_bf16 v[54:57], v[114:117], v[156:159], v[54:57]
	v_mfma_f32_16x16x32_bf16 v[50:53], v[122:125], v[156:159], v[50:53]
	v_mfma_f32_16x16x32_bf16 v[86:89], v[118:121], v[134:137], v[86:89]
	v_mfma_f32_16x16x32_bf16 v[82:85], v[126:129], v[134:137], v[82:85]
	v_mfma_f32_16x16x32_bf16 v[70:73], v[118:121], v[152:155], v[70:73]
	v_mfma_f32_16x16x32_bf16 v[66:69], v[126:129], v[152:155], v[66:69]
	v_mfma_f32_16x16x32_bf16 v[54:57], v[118:121], v[160:163], v[54:57]
	v_mfma_f32_16x16x32_bf16 v[50:53], v[126:129], v[160:163], v[50:53]
	s_barrier
	s_setprio 0
	s_mov_b32 m0, s27
	v_lshl_add_u64 v[164:165], s[18:19], 0, v[0:1]
	s_add_u32 s14, s18, 0x160000
	ds_read_b128 v[130:133], v167 offset:16384
	ds_read_b128 v[134:137], v167 offset:17408
	ds_read_b128 v[138:141], v167 offset:18432
	ds_read_b128 v[152:155], v167 offset:19456
	ds_read_b128 v[156:159], v167 offset:20480
	ds_read_b128 v[160:163], v167 offset:21504
	global_load_lds_dwordx4 v0, s[18:19]
	v_lshl_add_u64 v[168:169], s[18:19], 0, v[146:147]
	s_mov_b32 m0, s28
	s_addc_u32 s15, s19, 0
	global_load_lds_dwordx4 v146, s[18:19]
	s_mov_b32 m0, s30
	v_lshl_add_u64 v[172:173], s[20:21], 0, v[144:145]
	global_load_lds_dwordx4 v0, s[14:15]
	s_mov_b32 m0, s31
	s_nop 0
	global_load_lds_dwordx4 v146, s[14:15]
	v_lshl_add_u64 v[170:171], s[20:21], 0, v[142:143]
	s_mov_b32 m0, s34
	s_nop 0
	global_load_lds_dwordx4 v142, s[20:21]
	s_mov_b32 m0, s35
	s_nop 0
	s_and_b64 vcc, exec, s[8:9]
	s_cbranch_vccz .Lnm3d_skip1
	global_load_lds_dwordx4 v144, s[20:21]
	s_waitcnt vmcnt(8)
	s_branch .Lnm3d_done1

; #define PG8_STAGE(bufoff, gbase, voff) do { _Pragma("unroll") for (int _i = 0; _i < 2; ++_i) \
;         __builtin_amdgcn_global_load_lds((const unsigned*)((const char*)(gbase) + (voff)[_i]), (LAS unsigned*)(lds + (bufoff) + ldsw + _i * 8192), 16, 0, 0); } while (0)
; #define PG8_LDA(dst, b, h) do { _Pragma("unroll") for (int m = 0; m < NM; ++m) _Pragma("unroll") for (int k = 0; k < 2; ++k) dst[m][k] = *(const LAS bf16x8*)(lds + PG8_SA(b, h) + aoff + m * 2048 + k * 1024); } while (0)
; #define PG8_LDB(dst, b, h) do { _Pragma("unroll") for (int n = 0; n < 2; ++n) _Pragma("unroll") for (int k = 0; k < 2; ++k) dst[n][k] = *(const LAS bf16x8*)(lds + PG8_SB(b, h) + boff + n * 2048 + k * 1024); } while (0)
; #define PG8_MMA(ai, bj, At, Bt) do { __builtin_amdgcn_s_setprio(1); _Pragma("unroll") for (int m = 0; m < NM; ++m) _Pragma("unroll") for (int n = 0; n < 2; ++n) _Pragma("unroll") for (int k = 0; k < 2; ++k) \
;         acc[ai][bj][m][n] = __builtin_amdgcn_mfma_f32_16x16x32_bf16(Bt[n][k], At[m][k], acc[ai][bj][m][n], 0, 0, 0); __builtin_amdgcn_s_setprio(0); } while (0)
; #define PG8_WAIT_V(n) asm volatile("s_waitcnt vmcnt(" #n ")" ::: "memory")
; #define PG8_WAIT_L(n) asm volatile("s_waitcnt lgkmcnt(" #n ")" ::: "memory")
; #define PG8_BAR __builtin_amdgcn_s_barrier()
; #define PG8_SCHED __builtin_amdgcn_sched_barrier(0)
;     ...
;             PG8_WAIT_V(8); PG8_WAIT_L(0); PG8_BAR; PG8_MMA(1, 0, At, B0); PG8_MMA(1, 1, At, B1); PG8_BAR; PG8_SCHED;
;             PG8_LDB(B0, 1, 0); PG8_LDB(B1, 1, 1); PG8_SCHED; PG8_LDA(At, 1, 0); PG8_STAGE(PG8_SA(0, 1), a2 + hstepA, voffA);
.Lnm3d_done1:
	s_waitcnt lgkmcnt(0)
	s_setprio 1
	s_barrier
	v_mfma_f32_16x16x32_bf16 v[46:49], v[90:93], v[130:133], v[46:49]
	v_mfma_f32_16x16x32_bf16 v[42:45], v[98:101], v[130:133], v[42:45]
	v_mfma_f32_16x16x32_bf16 v[30:33], v[90:93], v[138:141], v[30:33]
	v_mfma_f32_16x16x32_bf16 v[26:29], v[98:101], v[138:141], v[26:29]
	v_mfma_f32_16x16x32_bf16 v[14:17], v[90:93], v[156:159], v[14:17]
	v_mfma_f32_16x16x32_bf16 v[10:13], v[98:101], v[156:159], v[10:13]
	v_mfma_f32_16x16x32_bf16 v[46:49], v[94:97], v[134:137], v[46:49]
	v_mfma_f32_16x16x32_bf16 v[42:45], v[102:105], v[134:137], v[42:45]
	v_mfma_f32_16x16x32_bf16 v[30:33], v[94:97], v[152:155], v[30:33]
	v_mfma_f32_16x16x32_bf16 v[26:29], v[102:105], v[152:155], v[26:29]
	v_mfma_f32_16x16x32_bf16 v[14:17], v[94:97], v[160:163], v[14:17]
	v_mfma_f32_16x16x32_bf16 v[10:13], v[102:105], v[160:163], v[10:13]
	s_setprio 0
	s_setprio 1
	v_mfma_f32_16x16x32_bf16 v[38:41], v[114:117], v[130:133], v[38:41]
	v_mfma_f32_16x16x32_bf16 v[34:37], v[122:125], v[130:133], v[34:37]
	v_mfma_f32_16x16x32_bf16 v[22:25], v[114:117], v[138:141], v[22:25]
	v_mfma_f32_16x16x32_bf16 v[18:21], v[122:125], v[138:141], v[18:21]
	v_mfma_f32_16x16x32_bf16 v[6:9], v[114:117], v[156:159], v[6:9]
	v_mfma_f32_16x16x32_bf16 v[2:5], v[122:125], v[156:159], v[2:5]
	v_mfma_f32_16x16x32_bf16 v[38:41], v[118:121], v[134:137], v[38:41]
	v_mfma_f32_16x16x32_bf16 v[34:37], v[126:129], v[134:137], v[34:37]
	v_mfma_f32_16x16x32_bf16 v[22:25], v[118:121], v[152:155], v[22:25]
	v_mfma_f32_16x16x32_bf16 v[18:21], v[126:129], v[152:155], v[18:21]
	v_mfma_f32_16x16x32_bf16 v[6:9], v[118:121], v[160:163], v[6:9]
	v_mfma_f32_16x16x32_bf16 v[2:5], v[126:129], v[160:163], v[2:5]
	s_barrier
	s_setprio 0
	v_add_u32_e32 v102, s38, v166
	v_add_u32_e32 v126, s45, v166
	ds_read_b128 v[90:93], v102
	ds_read_b128 v[94:97], v102 offset:1024
	ds_read_b128 v[98:101], v102 offset:2048
	ds_read_b128 v[102:105], v102 offset:3072
	ds_read_b128 v[114:117], v126
	ds_read_b128 v[118:121], v126 offset:1024
	ds_read_b128 v[122:125], v126 offset:2048
	ds_read_b128 v[126:129], v126 offset:3072
	s_add_u32 s14, s20, 0x108000
	s_addc_u32 s15, s21, 0
	s_mov_b32 m0, s36
	ds_read_b128 v[130:133], v167 offset:32768
	ds_read_b128 v[134:137], v167 offset:33792
	ds_read_b128 v[138:141], v167 offset:34816
	ds_read_b128 v[152:155], v167 offset:35840
	ds_read_b128 v[156:159], v167 offset:36864
	ds_read_b128 v[160:163], v167 offset:37888
	global_load_lds_dwordx4 v142, s[14:15]
	s_mov_b32 m0, s37
	s_nop 0
	s_and_b64 vcc, exec, s[8:9]
	s_cbranch_vccz .Lnm3d_skip2
	global_load_lds_dwordx4 v144, s[14:15]
	s_waitcnt vmcnt(8)
	s_branch .Lnm3d_done2

; #define PG8_STAGE(bufoff, gbase, voff) do { _Pragma("unroll") for (int _i = 0; _i < 2; ++_i) \
;         __builtin_amdgcn_global_load_lds((const unsigned*)((const char*)(gbase) + (voff)[_i]), (LAS unsigned*)(lds + (bufoff) + ldsw + _i * 8192), 16, 0, 0); } while (0)
; #define PG8_LDA(dst, b, h) do { _Pragma("unroll") for (int m = 0; m < NM; ++m) _Pragma("unroll") for (int k = 0; k < 2; ++k) dst[m][k] = *(const LAS bf16x8*)(lds + PG8_SA(b, h) + aoff + m * 2048 + k * 1024); } while (0)
; #define PG8_MMA(ai, bj, At, Bt) do { __builtin_amdgcn_s_setprio(1); _Pragma("unroll") for (int m = 0; m < NM; ++m) _Pragma("unroll") for (int n = 0; n < 2; ++n) _Pragma("unroll") for (int k = 0; k < 2; ++k) \
;         acc[ai][bj][m][n] = __builtin_amdgcn_mfma_f32_16x16x32_bf16(Bt[n][k], At[m][k], acc[ai][bj][m][n], 0, 0, 0); __builtin_amdgcn_s_setprio(0); } while (0)
; #define PG8_WAIT_V(n) asm volatile("s_waitcnt vmcnt(" #n ")" ::: "memory")
; #define PG8_WAIT_L(n) asm volatile("s_waitcnt lgkmcnt(" #n ")" ::: "memory")
; #define PG8_BAR __builtin_amdgcn_s_barrier()
; #define PG8_SCHED __builtin_amdgcn_sched_barrier(0)
;     ...
;             PG8_WAIT_V(8); PG8_WAIT_L(0); PG8_BAR; PG8_MMA(0, 0, At, B0); PG8_MMA(0, 1, At, B1); PG8_BAR; PG8_SCHED;
;             PG8_LDA(At, 1, 1); PG8_STAGE(PG8_SB(1, 0), b3, voffB); PG8_STAGE(PG8_SB(1, 1), b3 + hstepB, voffB); PG8_STAGE(PG8_SA(1, 0), a3, voffA);
;             PG8_WAIT_V(8); PG8_WAIT_L(0); PG8_BAR; PG8_MMA(1, 0, At, B0); PG8_MMA(1, 1, At, B1); PG8_BAR; PG8_SCHED;
.Lnm3d_done2:
	s_waitcnt lgkmcnt(0)
	s_setprio 1
	s_barrier
	v_mfma_f32_16x16x32_bf16 v[110:113], v[90:93], v[130:133], v[110:113]
	v_mfma_f32_16x16x32_bf16 v[106:109], v[98:101], v[130:133], v[106:109]
	v_mfma_f32_16x16x32_bf16 v[78:81], v[90:93], v[138:141], v[78:81]
	v_mfma_f32_16x16x32_bf16 v[74:77], v[98:101], v[138:141], v[74:77]
	v_mfma_f32_16x16x32_bf16 v[62:65], v[90:93], v[156:159], v[62:65]
	v_mfma_f32_16x16x32_bf16 v[58:61], v[98:101], v[156:159], v[58:61]
	v_mfma_f32_16x16x32_bf16 v[110:113], v[94:97], v[134:137], v[110:113]
	v_mfma_f32_16x16x32_bf16 v[106:109], v[102:105], v[134:137], v[106:109]
	v_mfma_f32_16x16x32_bf16 v[78:81], v[94:97], v[152:155], v[78:81]
	v_mfma_f32_16x16x32_bf16 v[74:77], v[102:105], v[152:155], v[74:77]
	v_mfma_f32_16x16x32_bf16 v[62:65], v[94:97], v[160:163], v[62:65]
	v_mfma_f32_16x16x32_bf16 v[58:61], v[102:105], v[160:163], v[58:61]
	s_setprio 0
	s_setprio 1
	v_mfma_f32_16x16x32_bf16 v[86:89], v[114:117], v[130:133], v[86:89]
	v_mfma_f32_16x16x32_bf16 v[82:85], v[122:125], v[130:133], v[82:85]
	v_mfma_f32_16x16x32_bf16 v[70:73], v[114:117], v[138:141], v[70:73]
	v_mfma_f32_16x16x32_bf16 v[66:69], v[122:125], v[138:141], v[66:69]
	v_mfma_f32_16x16x32_bf16 v[54:57], v[114:117], v[156:159], v[54:57]
	v_mfma_f32_16x16x32_bf16 v[50:53], v[122:125], v[156:159], v[50:53]
	v_mfma_f32_16x16x32_bf16 v[86:89], v[118:121], v[134:137], v[86:89]
	v_mfma_f32_16x16x32_bf16 v[82:85], v[126:129], v[134:137], v[82:85]
	v_mfma_f32_16x16x32_bf16 v[70:73], v[118:121], v[152:155], v[70:73]
	v_mfma_f32_16x16x32_bf16 v[66:69], v[126:129], v[152:155], v[66:69]
	v_mfma_f32_16x16x32_bf16 v[54:57], v[118:121], v[160:163], v[54:57]
	v_mfma_f32_16x16x32_bf16 v[50:53], v[126:129], v[160:163], v[50:53]
	s_barrier
	s_setprio 0
	s_mov_b32 m0, s41
	v_lshl_add_u64 v[164:165], v[164:165], 0, s[66:67]
	s_add_u32 s14, s18, 0x160080
	ds_read_b128 v[130:133], v167 offset:49152
	ds_read_b128 v[134:137], v167 offset:50176
	ds_read_b128 v[138:141], v167 offset:51200
	ds_read_b128 v[152:155], v167 offset:52224
	ds_read_b128 v[156:159], v167 offset:53248
	ds_read_b128 v[160:163], v167 offset:54272
	global_load_lds_dwordx4 v[164:165], off
	v_lshl_add_u64 v[164:165], v[168:169], 0, s[66:67]
	s_mov_b32 m0, s42
	s_addc_u32 s15, s19, 0
	global_load_lds_dwordx4 v[164:165], off
	s_mov_b32 m0, s46
	s_nop 0
	global_load_lds_dwordx4 v0, s[14:15]
	s_mov_b32 m0, s47
	s_nop 0
	global_load_lds_dwordx4 v146, s[14:15]
	v_lshl_add_u64 v[164:165], v[170:171], 0, s[66:67]
	s_mov_b32 m0, s43
	s_nop 0
	global_load_lds_dwordx4 v[164:165], off
	v_lshl_add_u64 v[164:165], v[172:173], 0, s[66:67]
	s_mov_b32 m0, s44
	s_nop 0
	s_and_b64 vcc, exec, s[8:9]
	s_cbranch_vccz .Lnm3d_skip3
	global_load_lds_dwordx4 v[164:165], off
	s_waitcnt vmcnt(8)
	s_branch .Lnm3d_done3
.Lnm3d_skip3:
	s_waitcnt vmcnt(6)
.Lnm3d_done3:
	s_waitcnt lgkmcnt(0)
	s_setprio 1
	s_barrier
	v_mfma_f32_16x16x32_bf16 v[46:49], v[90:93], v[130:133], v[46:49]
	v_mfma_f32_16x16x32_bf16 v[42:45], v[98:101], v[130:133], v[42:45]
	v_mfma_f32_16x16x32_bf16 v[30:33], v[90:93], v[138:141], v[30:33]
	v_mfma_f32_16x16x32_bf16 v[26:29], v[98:101], v[138:141], v[26:29]
	v_mfma_f32_16x16x32_bf16 v[14:17], v[90:93], v[156:159], v[14:17]
	v_mfma_f32_16x16x32_bf16 v[10:13], v[98:101], v[156:159], v[10:13]
	v_mfma_f32_16x16x32_bf16 v[46:49], v[94:97], v[134:137], v[46:49]
	v_mfma_f32_16x16x32_bf16 v[42:45], v[102:105], v[134:137], v[42:45]
	v_mfma_f32_16x16x32_bf16 v[30:33], v[94:97], v[152:155], v[30:33]
	v_mfma_f32_16x16x32_bf16 v[26:29], v[102:105], v[152:155], v[26:29]
	v_mfma_f32_16x16x32_bf16 v[14:17], v[94:97], v[160:163], v[14:17]
	v_mfma_f32_16x16x32_bf16 v[10:13], v[102:105], v[160:163], v[10:13]
	s_setprio 0
	s_setprio 1
	v_mfma_f32_16x16x32_bf16 v[38:41], v[114:117], v[130:133], v[38:41]
	v_mfma_f32_16x16x32_bf16 v[34:37], v[122:125], v[130:133], v[34:37]
	v_mfma_f32_16x16x32_bf16 v[22:25], v[114:117], v[138:141], v[22:25]
	v_mfma_f32_16x16x32_bf16 v[18:21], v[122:125], v[138:141], v[18:21]
	v_mfma_f32_16x16x32_bf16 v[6:9], v[114:117], v[156:159], v[6:9]
	v_mfma_f32_16x16x32_bf16 v[2:5], v[122:125], v[156:159], v[2:5]
	v_mfma_f32_16x16x32_bf16 v[38:41], v[118:121], v[134:137], v[38:41]
	v_mfma_f32_16x16x32_bf16 v[34:37], v[126:129], v[134:137], v[34:37]
	v_mfma_f32_16x16x32_bf16 v[22:25], v[118:121], v[152:155], v[22:25]
	v_mfma_f32_16x16x32_bf16 v[18:21], v[126:129], v[152:155], v[18:21]
	v_mfma_f32_16x16x32_bf16 v[6:9], v[118:121], v[160:163], v[6:9]
	v_mfma_f32_16x16x32_bf16 v[2:5], v[126:129], v[160:163], v[2:5]
	s_barrier
	s_setprio 0
	s_add_i32 s60, s60, 2
	s_add_u32 s2, s2, 0x100
	s_addc_u32 s3, s3, 0
	s_cmpk_gt_u32 s60, 0x55
	s_mov_b64 s[14:15], s[16:17]
	s_cbranch_scc0 .LBB0_2158
	s_and_b64 vcc, exec, s[8:9]
	s_cbranch_vccz .LBB0_2161
	s_barrier
